# diff-attention loop: waves 0-3 pack the matrix ops into the first half of the softmax stream and waves 4-7 into the second half; V fragments read one key step ahead
# baseline (speedup 1.0000x reference)
.LBB0_506:
	s_lshr_b32 s98, s64, 2
	s_mul_i32 s1, s90, 0xa00000
	s_mul_hi_i32 s0, s90, 0xa00000
	s_add_u32 s1, s86, s1
	v_writelane_b32 v254, s70, 54
	s_addc_u32 s0, s87, s0
	s_add_u32 s1, s1, 0x9800000
	v_writelane_b32 v254, s71, 55
	v_writelane_b32 v254, s1, 56
	s_addc_u32 s0, s0, 0
	v_writelane_b32 v254, s0, 58
	s_lshl_b32 s0, s90, 7
	s_ashr_i32 s1, s0, 31
	s_lshl_b64 s[0:1], s[0:1], 2
	s_add_u32 s30, s86, s0
	s_addc_u32 s31, s87, s1
	v_readlane_b32 s5, v254, 20
	s_cmp_gt_u32 s5, 63
	s_cselect_b64 s[0:1], -1, 0
	v_writelane_b32 v254, s0, 60
	s_cmp_lt_u32 s5, 64
	s_cselect_b32 s38, 16, 0
	v_writelane_b32 v254, s1, 61
	s_mul_i32 s0, s64, 0x2400
	s_bfe_u32 s1, s5, 0x20006
	s_add_i32 s39, s0, 0
	s_lshr_b32 s0, s5, 8
	s_lshl_b32 s42, s1, 5
	s_bfe_u32 s4, s64, 0x10001
	s_lshl_b32 s1, s1, 14
	v_writelane_b32 v254, s4, 62
	s_lshl_b32 s4, s0, 6
	s_lshl_b32 s6, s0, 7
	s_add_i32 s1, s1, 0
	s_cmp_eq_u32 s0, 1
	v_writelane_b32 v255, s6, 0
	s_cselect_b64 s[6:7], -1, 0
	v_writelane_b32 v255, s6, 2
	s_cmpk_lt_u32 s5, 0x100
	v_bfe_u32 v0, v180, 5, 1
	v_writelane_b32 v255, s7, 3
	v_lshl_add_u32 v211, v253, 2, s1
	s_cselect_b64 s[0:1], -1, 0
	v_lshlrev_b32_e32 v2, 3, v0
	v_mov_b32_e32 v1, 0
	v_writelane_b32 v255, s0, 4
	v_lshlrev_b32_e32 v4, 2, v0
	v_lshlrev_b32_e32 v0, 4, v0
	v_min_i32_e32 v212, 15, v230
	s_mov_b32 s71, 0
	v_writelane_b32 v255, s1, 5
	v_lshl_add_u64 v[186:187], s[24:25], 0, v[0:1]
	s_add_i32 s91, 0, 0x20000
	s_add_i32 s0, 0, 0x20004
	v_mbcnt_lo_u32_b32 v0, -1, 0
	v_or_b32_e32 v210, 0x4000, v212
	s_mov_b32 s43, s71
	s_add_i32 s90, s39, 0x10000
	s_movk_i32 s20, 0x1800
	s_movk_i32 s21, 0x1000
	s_movk_i32 s22, 0x78
	s_movk_i32 s44, 0xc0
	s_mov_b32 s45, 0x42b50000
	s_movk_i32 s46, 0x110
	s_add_i32 s47, 0, 0x20008
	s_movk_i32 s26, 0x3000
	s_lshl_b32 s48, s4, 1
	s_mov_b32 s27, 0x42800000
	v_lshlrev_b32_e32 v188, 1, v4
	v_writelane_b32 v255, s0, 6
	v_mov_b32_e32 v213, s91
	v_lshlrev_b32_e32 v190, 1, v2
	v_mov_b32_e32 v214, 0xf149f2ca
	v_mov_b32_e32 v215, 0x6fce03f9
	v_mov_b32_e32 v216, 0x1800
	v_mbcnt_hi_u32_b32 v217, -1, v0
	v_mov_b32_e32 v218, 0x4000
	s_mov_b64 s[58:59], 0
	s_mov_b64 s[50:51], 0xb220800
	s_mov_b64 s[52:53], 0xb220400
	s_mov_b64 s[54:55], 0xb280800
	s_mov_b64 s[56:57], 0xb280400
	s_mov_b64 s[88:89], 0x40000
	s_branch .LBB0_510

.Lnl_me:
	s_cmp_lg_u32 s98, 0
	s_cbranch_scc1 .Lnl_B_e
	v_cmp_gt_f32_e32 vcc, 1.0, v194
	s_cbranch_vccz .Lnl_nors_ea
	v_pk_mul_f32 v[78:79], v[78:79], v[194:195] op_sel_hi:[1,0]
	v_pk_mul_f32 v[76:77], v[76:77], v[194:195] op_sel_hi:[1,0]
	v_pk_mul_f32 v[74:75], v[74:75], v[194:195] op_sel_hi:[1,0]
	v_pk_mul_f32 v[72:73], v[72:73], v[194:195] op_sel_hi:[1,0]
	v_pk_mul_f32 v[70:71], v[70:71], v[194:195] op_sel_hi:[1,0]
	v_pk_mul_f32 v[68:69], v[68:69], v[194:195] op_sel_hi:[1,0]
	v_pk_mul_f32 v[66:67], v[66:67], v[194:195] op_sel_hi:[1,0]
	v_pk_mul_f32 v[64:65], v[64:65], v[194:195] op_sel_hi:[1,0]
	v_pk_mul_f32 v[62:63], v[62:63], v[194:195] op_sel_hi:[1,0]
	v_pk_mul_f32 v[60:61], v[60:61], v[194:195] op_sel_hi:[1,0]
	v_pk_mul_f32 v[58:59], v[58:59], v[194:195] op_sel_hi:[1,0]
	v_pk_mul_f32 v[56:57], v[56:57], v[194:195] op_sel_hi:[1,0]
	v_pk_mul_f32 v[54:55], v[54:55], v[194:195] op_sel_hi:[1,0]
	v_pk_mul_f32 v[52:53], v[52:53], v[194:195] op_sel_hi:[1,0]
	v_pk_mul_f32 v[50:51], v[50:51], v[194:195] op_sel_hi:[1,0]
	v_pk_mul_f32 v[48:49], v[48:49], v[194:195] op_sel_hi:[1,0]
	v_pk_mul_f32 v[46:47], v[46:47], v[194:195] op_sel_hi:[1,0]
	v_pk_mul_f32 v[44:45], v[44:45], v[194:195] op_sel_hi:[1,0]
	v_pk_mul_f32 v[42:43], v[42:43], v[194:195] op_sel_hi:[1,0]
	v_pk_mul_f32 v[40:41], v[40:41], v[194:195] op_sel_hi:[1,0]
	v_pk_mul_f32 v[38:39], v[38:39], v[194:195] op_sel_hi:[1,0]
	v_pk_mul_f32 v[36:37], v[36:37], v[194:195] op_sel_hi:[1,0]
	v_pk_mul_f32 v[34:35], v[34:35], v[194:195] op_sel_hi:[1,0]
	v_pk_mul_f32 v[32:33], v[32:33], v[194:195] op_sel_hi:[1,0]
	v_pk_mul_f32 v[30:31], v[30:31], v[194:195] op_sel_hi:[1,0]
	v_pk_mul_f32 v[28:29], v[28:29], v[194:195] op_sel_hi:[1,0]
	v_pk_mul_f32 v[26:27], v[26:27], v[194:195] op_sel_hi:[1,0]
	v_pk_mul_f32 v[24:25], v[24:25], v[194:195] op_sel_hi:[1,0]
	v_pk_mul_f32 v[22:23], v[22:23], v[194:195] op_sel_hi:[1,0]
	v_pk_mul_f32 v[20:21], v[20:21], v[194:195] op_sel_hi:[1,0]
	v_pk_mul_f32 v[18:19], v[18:19], v[194:195] op_sel_hi:[1,0]
	v_pk_mul_f32 v[16:17], v[16:17], v[194:195] op_sel_hi:[1,0]
.Lnl_nors_ea:
	v_max_f32_e32 v206, v81, v81
	v_max_f32_e32 v207, v80, v80
	v_max_f32_e32 v206, v207, v206
	ds_read_b64_tr_b16 v[160:161], v13 offset:4096
	ds_read_b64_tr_b16 v[162:163], v13 offset:6144
	ds_read_b64_tr_b16 v[182:183], v13 offset:4608
	ds_read_b64_tr_b16 v[184:185], v13 offset:6656
	ds_read_b64_tr_b16 v[198:199], v13 offset:5120
	ds_read_b64_tr_b16 v[200:201], v13 offset:7168
	ds_read_b64_tr_b16 v[202:203], v13 offset:5632
	ds_read_b64_tr_b16 v[204:205], v13 offset:7680
	v_max3_f32 v206, v206, v82, v83
	v_max3_f32 v206, v206, v84, v85
	s_waitcnt lgkmcnt(8)
	v_max3_f32 v206, v206, v86, v87
	v_max3_f32 v206, v206, v88, v89
	v_max3_f32 v206, v206, v90, v91
	v_mfma_f32_32x32x16_bf16 v[64:79], v[128:131], v[112:115], v[64:79]
	v_max3_f32 v206, v206, v92, v93
	v_max3_f32 v206, v206, v94, v95
	v_max3_f32 v206, v206, v96, v97
	v_mfma_f32_32x32x16_bf16 v[48:63], v[132:135], v[112:115], v[48:63]
	v_max3_f32 v206, v206, v98, v99
	v_max3_f32 v206, v206, v100, v101
	v_mfma_f32_32x32x16_bf16 v[32:47], v[136:139], v[112:115], v[32:47]
	v_max3_f32 v206, v206, v102, v103
	v_max3_f32 v206, v206, v104, v105
	v_max3_f32 v206, v206, v106, v107
	v_mfma_f32_32x32x16_bf16 v[16:31], v[140:143], v[112:115], v[16:31]
	v_max3_f32 v206, v206, v108, v109
	v_max3_f32 v206, v206, v110, v111
	v_mov_b32_e32 v207, v206
	ds_read_b64_tr_b16 v[128:129], v13 offset:8192
	ds_read_b64_tr_b16 v[130:131], v13 offset:10240
	ds_read_b64_tr_b16 v[132:133], v13 offset:8704
	ds_read_b64_tr_b16 v[134:135], v13 offset:10752
	ds_read_b64_tr_b16 v[136:137], v13 offset:9216
	ds_read_b64_tr_b16 v[138:139], v13 offset:11264
	ds_read_b64_tr_b16 v[140:141], v13 offset:9728
	ds_read_b64_tr_b16 v[142:143], v13 offset:11776
	s_nop 1
	v_permlane32_swap_b32_e32 v206, v207
	s_waitcnt lgkmcnt(8)
	v_max_f32_e32 v207, v207, v207
	v_max_f32_e32 v206, v206, v206
	v_max_f32_e32 v206, v206, v207
	v_mfma_f32_32x32x16_bf16 v[64:79], v[160:163], v[116:119], v[64:79]
	v_sub_f32_e32 v207, v206, v193
	v_cmp_ge_f32_e64 s[0:1], s27, v207
	v_max_f32_e32 v206, v206, v206
	v_mfma_f32_32x32x16_bf16 v[48:63], v[182:185], v[116:119], v[48:63]
	v_max_f32_e32 v207, v193, v193
	v_max_f32_e32 v206, v207, v206
	v_mfma_f32_32x32x16_bf16 v[32:47], v[198:201], v[116:119], v[32:47]
	s_cmp_eq_u64 s[0:1], exec
	s_cselect_b64 s[0:1], -1, 0
	v_cndmask_b32_e64 v14, v206, v193, s[0:1]
	v_mul_f32_e32 v207, 0xbe38aa3b, v14
	v_mfma_f32_32x32x16_bf16 v[16:31], v[202:205], v[116:119], v[16:31]
	v_fmamk_f32 v174, v80, 0x3e38aa3b, v207
	v_exp_f32_e32 v80, v174
	v_fmamk_f32 v174, v81, 0x3e38aa3b, v207
	ds_read_b64_tr_b16 v[160:161], v13 offset:12288
	ds_read_b64_tr_b16 v[162:163], v13 offset:14336
	ds_read_b64_tr_b16 v[182:183], v13 offset:12800
	ds_read_b64_tr_b16 v[184:185], v13 offset:14848
	ds_read_b64_tr_b16 v[198:199], v13 offset:13312
	ds_read_b64_tr_b16 v[200:201], v13 offset:15360
	ds_read_b64_tr_b16 v[202:203], v13 offset:13824
	ds_read_b64_tr_b16 v[204:205], v13 offset:15872
	v_exp_f32_e32 v81, v174
	v_fmamk_f32 v174, v82, 0x3e38aa3b, v207
	s_waitcnt lgkmcnt(8)
	v_exp_f32_e32 v82, v174
	v_fmamk_f32 v174, v83, 0x3e38aa3b, v207
	v_exp_f32_e32 v83, v174
	v_mfma_f32_32x32x16_bf16 v[64:79], v[128:131], v[120:123], v[64:79]
	v_fmamk_f32 v174, v84, 0x3e38aa3b, v207
	v_exp_f32_e32 v84, v174
	v_fmamk_f32 v174, v85, 0x3e38aa3b, v207
	v_mfma_f32_32x32x16_bf16 v[48:63], v[132:135], v[120:123], v[48:63]
	v_exp_f32_e32 v85, v174
	v_fmamk_f32 v174, v86, 0x3e38aa3b, v207
	v_exp_f32_e32 v86, v174
	v_mfma_f32_32x32x16_bf16 v[32:47], v[136:139], v[120:123], v[32:47]
	v_fmamk_f32 v174, v87, 0x3e38aa3b, v207
	v_exp_f32_e32 v87, v174
	v_mfma_f32_32x32x16_bf16 v[16:31], v[140:143], v[120:123], v[16:31]
	v_fmamk_f32 v174, v88, 0x3e38aa3b, v207
	v_exp_f32_e32 v88, v174
	v_fmamk_f32 v174, v89, 0x3e38aa3b, v207
	s_waitcnt lgkmcnt(0)
	v_exp_f32_e32 v89, v174
	v_fmamk_f32 v174, v90, 0x3e38aa3b, v207
	v_exp_f32_e32 v90, v174
	v_mfma_f32_32x32x16_bf16 v[64:79], v[160:163], v[124:127], v[64:79]
	v_fmamk_f32 v174, v91, 0x3e38aa3b, v207
	v_exp_f32_e32 v91, v174
	v_mfma_f32_32x32x16_bf16 v[48:63], v[182:185], v[124:127], v[48:63]
	v_fmamk_f32 v174, v92, 0x3e38aa3b, v207
	v_exp_f32_e32 v92, v174
	v_fmamk_f32 v174, v93, 0x3e38aa3b, v207
	v_mfma_f32_32x32x16_bf16 v[32:47], v[198:201], v[124:127], v[32:47]
	v_exp_f32_e32 v93, v174
	v_fmamk_f32 v174, v94, 0x3e38aa3b, v207
	v_exp_f32_e32 v94, v174
	v_mfma_f32_32x32x16_bf16 v[16:31], v[202:205], v[124:127], v[16:31]
	v_fmamk_f32 v174, v95, 0x3e38aa3b, v207
	v_exp_f32_e32 v95, v174
	s_add_i32 s6, s10, 0x8000
	s_and_b32 s6, s6, 0x18000
	v_add_u32_e32 v0, s6, v175
	ds_read_b128 v[2:5], v0 offset:0
	ds_read_b128 v[6:9], v0 offset:8192
	v_add_u32_e32 v0, s6, v176
	ds_read_b128 v[10:13], v0 offset:0
	ds_read_b128 v[160:163], v0 offset:8192
	v_fmamk_f32 v174, v96, 0x3e38aa3b, v207
	v_exp_f32_e32 v96, v174
	v_fmamk_f32 v174, v97, 0x3e38aa3b, v207
	s_waitcnt lgkmcnt(0)
	v_mfma_f32_32x32x16_bf16 v[112:127], v[2:5], v[144:147], 0
	v_exp_f32_e32 v97, v174
	v_fmamk_f32 v174, v98, 0x3e38aa3b, v207
	v_exp_f32_e32 v98, v174
	v_add_u32_e32 v0, s6, v177
	ds_read_b128 v[2:5], v0 offset:0
	v_mfma_f32_32x32x16_bf16 v[128:143], v[6:9], v[144:147], 0
	ds_read_b128 v[6:9], v0 offset:8192
	v_fmamk_f32 v174, v99, 0x3e38aa3b, v207
	v_exp_f32_e32 v99, v174
	v_add_u32_e32 v0, s6, v189
	v_mfma_f32_32x32x16_bf16 v[112:127], v[10:13], v[148:151], v[112:127]
	ds_read_b128 v[10:13], v0 offset:0
	ds_read_b128 v[182:185], v0 offset:8192
	v_fmamk_f32 v174, v100, 0x3e38aa3b, v207
	v_exp_f32_e32 v100, v174
	v_fmamk_f32 v174, v101, 0x3e38aa3b, v207
	s_waitcnt lgkmcnt(0)
	v_mfma_f32_32x32x16_bf16 v[128:143], v[160:163], v[148:151], v[128:143]
	v_exp_f32_e32 v101, v174
	v_fmamk_f32 v174, v102, 0x3e38aa3b, v207
	v_exp_f32_e32 v102, v174
	v_mfma_f32_32x32x16_bf16 v[112:127], v[2:5], v[152:155], v[112:127]
	v_fmamk_f32 v174, v103, 0x3e38aa3b, v207
	v_exp_f32_e32 v103, v174
	v_mfma_f32_32x32x16_bf16 v[128:143], v[6:9], v[152:155], v[128:143]
	v_fmamk_f32 v174, v104, 0x3e38aa3b, v207
	v_exp_f32_e32 v104, v174
	v_fmamk_f32 v174, v105, 0x3e38aa3b, v207
	v_mfma_f32_32x32x16_bf16 v[112:127], v[10:13], v[156:159], v[112:127]
	v_exp_f32_e32 v105, v174
	v_fmamk_f32 v174, v106, 0x3e38aa3b, v207
	v_exp_f32_e32 v106, v174
	v_mfma_f32_32x32x16_bf16 v[128:143], v[182:185], v[156:159], v[128:143]
	v_fmamk_f32 v174, v107, 0x3e38aa3b, v207
	v_exp_f32_e32 v107, v174
	v_fmamk_f32 v174, v108, 0x3e38aa3b, v207
	v_exp_f32_e32 v108, v174
	v_fmamk_f32 v174, v109, 0x3e38aa3b, v207
	v_exp_f32_e32 v109, v174
	v_fmamk_f32 v174, v110, 0x3e38aa3b, v207
	v_exp_f32_e32 v110, v174
	v_fmamk_f32 v174, v111, 0x3e38aa3b, v207
	v_exp_f32_e32 v111, v174
	v_sub_f32_e32 v206, v193, v206
	v_mul_f32_e32 v206, 0x3e38aa3b, v206
	v_exp_f32_e32 v206, v206
	v_add_f32_e32 v207, 0, v80
	v_cndmask_b32_e64 v194, v206, 1.0, s[0:1]
	v_mov_b32_e32 v193, v14
	v_add_f32_e32 v207, v81, v207
	v_add_f32_e32 v207, v82, v207
	v_add_f32_e32 v207, v83, v207
	v_add_f32_e32 v207, v84, v207
	v_add_f32_e32 v207, v85, v207
	v_add_f32_e32 v207, v86, v207
	v_add_f32_e32 v207, v87, v207
	v_add_f32_e32 v207, v88, v207
	v_add_f32_e32 v207, v89, v207
	v_add_f32_e32 v207, v90, v207
	v_add_f32_e32 v207, v91, v207
	v_add_f32_e32 v207, v92, v207
	v_add_f32_e32 v207, v93, v207
	v_add_f32_e32 v207, v94, v207
	v_add_f32_e32 v207, v95, v207
	v_add_f32_e32 v207, v96, v207
	v_add_f32_e32 v207, v97, v207
	v_add_f32_e32 v207, v98, v207
	v_add_f32_e32 v207, v99, v207
	v_add_f32_e32 v207, v100, v207
	v_add_f32_e32 v207, v101, v207
	v_add_f32_e32 v207, v102, v207
	v_add_f32_e32 v207, v103, v207
	v_add_f32_e32 v207, v104, v207
	v_add_f32_e32 v207, v105, v207
	v_add_f32_e32 v207, v106, v207
	v_add_f32_e32 v207, v107, v207
	v_add_f32_e32 v207, v108, v207
	v_add_f32_e32 v207, v109, v207
	v_add_f32_e32 v207, v110, v207
	v_add_f32_e32 v15, v111, v207
	v_mov_b32_e32 v195, v15
	v_cvt_pk_bf16_f32 v80, v80, v81
	v_cvt_pk_bf16_f32 v81, v82, v83
	v_cvt_pk_bf16_f32 v82, v84, v85
	v_cvt_pk_bf16_f32 v83, v86, v87
	v_cvt_pk_bf16_f32 v84, v88, v89
	v_cvt_pk_bf16_f32 v85, v90, v91
	v_cvt_pk_bf16_f32 v86, v92, v93
	v_cvt_pk_bf16_f32 v87, v94, v95
	v_cvt_pk_bf16_f32 v88, v96, v97
	v_cvt_pk_bf16_f32 v89, v98, v99
	v_cvt_pk_bf16_f32 v90, v100, v101
	v_cvt_pk_bf16_f32 v91, v102, v103
	v_cvt_pk_bf16_f32 v92, v104, v105
	v_cvt_pk_bf16_f32 v93, v106, v107
	v_cvt_pk_bf16_f32 v94, v108, v109
	v_cvt_pk_bf16_f32 v95, v110, v111
	s_nop 1
	v_permlane32_swap_b32_e32 v15, v195
	v_permlane32_swap_b32_e32 v80, v82
	v_permlane32_swap_b32_e32 v81, v83
	v_permlane32_swap_b32_e32 v84, v86
	v_permlane32_swap_b32_e32 v85, v87
	v_permlane32_swap_b32_e32 v88, v90
	v_permlane32_swap_b32_e32 v89, v91
	v_permlane32_swap_b32_e32 v92, v94
	v_permlane32_swap_b32_e32 v93, v95
	v_add_f32_e32 v15, v15, v195
	v_fmac_f32_e32 v15, v192, v194
	v_mov_b32_e32 v192, v15
	s_add_i32 s0, s10, 0x0
	s_and_b32 s0, s0, 0x18000
	v_add_u32_e32 v13, s0, v191
	ds_read_b64_tr_b16 v[96:97], v13 offset:0
	ds_read_b64_tr_b16 v[98:99], v13 offset:2048
	ds_read_b64_tr_b16 v[100:101], v13 offset:512
	ds_read_b64_tr_b16 v[102:103], v13 offset:2560
	ds_read_b64_tr_b16 v[104:105], v13 offset:1024
	ds_read_b64_tr_b16 v[106:107], v13 offset:3072
	ds_read_b64_tr_b16 v[108:109], v13 offset:1536
	ds_read_b64_tr_b16 v[110:111], v13 offset:3584
	s_branch .Lnl_J_e

.Lnl_nors_eb:
	v_max_f32_e32 v206, v81, v81
	v_max_f32_e32 v207, v80, v80
	v_max_f32_e32 v206, v207, v206
	v_max3_f32 v206, v206, v82, v83
	v_max3_f32 v206, v206, v84, v85
	v_max3_f32 v206, v206, v86, v87
	v_max3_f32 v206, v206, v88, v89
	v_max3_f32 v206, v206, v90, v91
	v_max3_f32 v206, v206, v92, v93
	v_max3_f32 v206, v206, v94, v95
	v_max3_f32 v206, v206, v96, v97
	v_max3_f32 v206, v206, v98, v99
	v_max3_f32 v206, v206, v100, v101
	v_max3_f32 v206, v206, v102, v103
	v_max3_f32 v206, v206, v104, v105
	v_max3_f32 v206, v206, v106, v107
	v_max3_f32 v206, v206, v108, v109
	v_max3_f32 v206, v206, v110, v111
	v_mov_b32_e32 v207, v206
	s_nop 1
	v_permlane32_swap_b32_e32 v206, v207
	v_max_f32_e32 v207, v207, v207
	v_max_f32_e32 v206, v206, v206
	v_max_f32_e32 v206, v206, v207
	v_sub_f32_e32 v207, v206, v193
	v_cmp_ge_f32_e64 s[0:1], s27, v207
	v_max_f32_e32 v206, v206, v206
	v_max_f32_e32 v207, v193, v193
	v_max_f32_e32 v206, v207, v206
	s_cmp_eq_u64 s[0:1], exec
	s_cselect_b64 s[0:1], -1, 0
	v_cndmask_b32_e64 v14, v206, v193, s[0:1]
	v_mul_f32_e32 v207, 0xbe38aa3b, v14
	v_fmamk_f32 v174, v80, 0x3e38aa3b, v207
	v_exp_f32_e32 v80, v174
	v_fmamk_f32 v174, v81, 0x3e38aa3b, v207
	v_exp_f32_e32 v81, v174
	v_fmamk_f32 v174, v82, 0x3e38aa3b, v207
	v_exp_f32_e32 v82, v174
	v_fmamk_f32 v174, v83, 0x3e38aa3b, v207
	v_exp_f32_e32 v83, v174
	v_fmamk_f32 v174, v84, 0x3e38aa3b, v207
	v_exp_f32_e32 v84, v174
	v_fmamk_f32 v174, v85, 0x3e38aa3b, v207
	v_exp_f32_e32 v85, v174
	v_fmamk_f32 v174, v86, 0x3e38aa3b, v207
	v_exp_f32_e32 v86, v174
	v_fmamk_f32 v174, v87, 0x3e38aa3b, v207
	v_exp_f32_e32 v87, v174
	v_fmamk_f32 v174, v88, 0x3e38aa3b, v207
	v_exp_f32_e32 v88, v174
	v_fmamk_f32 v174, v89, 0x3e38aa3b, v207
	v_exp_f32_e32 v89, v174
	v_fmamk_f32 v174, v90, 0x3e38aa3b, v207
	v_exp_f32_e32 v90, v174
	v_fmamk_f32 v174, v91, 0x3e38aa3b, v207
	v_exp_f32_e32 v91, v174
	v_fmamk_f32 v174, v92, 0x3e38aa3b, v207
	v_exp_f32_e32 v92, v174
	v_fmamk_f32 v174, v93, 0x3e38aa3b, v207
	v_exp_f32_e32 v93, v174
	v_fmamk_f32 v174, v94, 0x3e38aa3b, v207
	v_exp_f32_e32 v94, v174
	v_fmamk_f32 v174, v95, 0x3e38aa3b, v207
	v_exp_f32_e32 v95, v174
	v_fmamk_f32 v174, v96, 0x3e38aa3b, v207
	v_exp_f32_e32 v96, v174
	v_fmamk_f32 v174, v97, 0x3e38aa3b, v207
	v_exp_f32_e32 v97, v174
	v_fmamk_f32 v174, v98, 0x3e38aa3b, v207
	v_exp_f32_e32 v98, v174
	v_fmamk_f32 v174, v99, 0x3e38aa3b, v207
	v_exp_f32_e32 v99, v174
	v_fmamk_f32 v174, v100, 0x3e38aa3b, v207
	ds_read_b64_tr_b16 v[160:161], v13 offset:4096
	ds_read_b64_tr_b16 v[162:163], v13 offset:6144
	ds_read_b64_tr_b16 v[182:183], v13 offset:4608
	ds_read_b64_tr_b16 v[184:185], v13 offset:6656
	ds_read_b64_tr_b16 v[198:199], v13 offset:5120
	ds_read_b64_tr_b16 v[200:201], v13 offset:7168
	ds_read_b64_tr_b16 v[202:203], v13 offset:5632
	ds_read_b64_tr_b16 v[204:205], v13 offset:7680
	v_exp_f32_e32 v100, v174
	v_fmamk_f32 v174, v101, 0x3e38aa3b, v207
	s_waitcnt lgkmcnt(8)
	v_exp_f32_e32 v101, v174
	v_fmamk_f32 v174, v102, 0x3e38aa3b, v207
	v_exp_f32_e32 v102, v174
	v_mfma_f32_32x32x16_bf16 v[64:79], v[128:131], v[112:115], v[64:79]
	v_fmamk_f32 v174, v103, 0x3e38aa3b, v207
	v_exp_f32_e32 v103, v174
	v_mfma_f32_32x32x16_bf16 v[48:63], v[132:135], v[112:115], v[48:63]
	v_fmamk_f32 v174, v104, 0x3e38aa3b, v207
	v_exp_f32_e32 v104, v174
	v_fmamk_f32 v174, v105, 0x3e38aa3b, v207
	v_mfma_f32_32x32x16_bf16 v[32:47], v[136:139], v[112:115], v[32:47]
	v_exp_f32_e32 v105, v174
	v_fmamk_f32 v174, v106, 0x3e38aa3b, v207
	v_mfma_f32_32x32x16_bf16 v[16:31], v[140:143], v[112:115], v[16:31]
	v_exp_f32_e32 v106, v174
	v_fmamk_f32 v174, v107, 0x3e38aa3b, v207
	v_exp_f32_e32 v107, v174
	ds_read_b64_tr_b16 v[128:129], v13 offset:8192
	ds_read_b64_tr_b16 v[130:131], v13 offset:10240
	ds_read_b64_tr_b16 v[132:133], v13 offset:8704
	ds_read_b64_tr_b16 v[134:135], v13 offset:10752
	ds_read_b64_tr_b16 v[136:137], v13 offset:9216
	ds_read_b64_tr_b16 v[138:139], v13 offset:11264
	ds_read_b64_tr_b16 v[140:141], v13 offset:9728
	ds_read_b64_tr_b16 v[142:143], v13 offset:11776
	v_fmamk_f32 v174, v108, 0x3e38aa3b, v207
	v_exp_f32_e32 v108, v174
	s_waitcnt lgkmcnt(8)
	v_fmamk_f32 v174, v109, 0x3e38aa3b, v207
	v_exp_f32_e32 v109, v174
	v_fmamk_f32 v174, v110, 0x3e38aa3b, v207
	v_mfma_f32_32x32x16_bf16 v[64:79], v[160:163], v[116:119], v[64:79]
	v_exp_f32_e32 v110, v174
	v_fmamk_f32 v174, v111, 0x3e38aa3b, v207
	v_exp_f32_e32 v111, v174
	v_mfma_f32_32x32x16_bf16 v[48:63], v[182:185], v[116:119], v[48:63]
	v_sub_f32_e32 v206, v193, v206
	v_mul_f32_e32 v206, 0x3e38aa3b, v206
	v_mfma_f32_32x32x16_bf16 v[32:47], v[198:201], v[116:119], v[32:47]
	v_exp_f32_e32 v206, v206
	v_add_f32_e32 v207, 0, v80
	v_cndmask_b32_e64 v194, v206, 1.0, s[0:1]
	v_mfma_f32_32x32x16_bf16 v[16:31], v[202:205], v[116:119], v[16:31]
	v_mov_b32_e32 v193, v14
	v_add_f32_e32 v207, v81, v207
	ds_read_b64_tr_b16 v[160:161], v13 offset:12288
	ds_read_b64_tr_b16 v[162:163], v13 offset:14336
	ds_read_b64_tr_b16 v[182:183], v13 offset:12800
	ds_read_b64_tr_b16 v[184:185], v13 offset:14848
	ds_read_b64_tr_b16 v[198:199], v13 offset:13312
	ds_read_b64_tr_b16 v[200:201], v13 offset:15360
	ds_read_b64_tr_b16 v[202:203], v13 offset:13824
	ds_read_b64_tr_b16 v[204:205], v13 offset:15872
	v_add_f32_e32 v207, v82, v207
	v_add_f32_e32 v207, v83, v207
	v_add_f32_e32 v207, v84, v207
	s_waitcnt lgkmcnt(8)
	v_add_f32_e32 v207, v85, v207
	v_add_f32_e32 v207, v86, v207
	v_mfma_f32_32x32x16_bf16 v[64:79], v[128:131], v[120:123], v[64:79]
	v_add_f32_e32 v207, v87, v207
	v_add_f32_e32 v207, v88, v207
	v_add_f32_e32 v207, v89, v207
	v_mfma_f32_32x32x16_bf16 v[48:63], v[132:135], v[120:123], v[48:63]
	v_add_f32_e32 v207, v90, v207
	v_add_f32_e32 v207, v91, v207
	v_add_f32_e32 v207, v92, v207
	v_mfma_f32_32x32x16_bf16 v[32:47], v[136:139], v[120:123], v[32:47]
	v_add_f32_e32 v207, v93, v207
	v_add_f32_e32 v207, v94, v207
	v_mfma_f32_32x32x16_bf16 v[16:31], v[140:143], v[120:123], v[16:31]
	v_add_f32_e32 v207, v95, v207
	v_add_f32_e32 v207, v96, v207
	v_add_f32_e32 v207, v97, v207
	s_waitcnt lgkmcnt(0)
	v_add_f32_e32 v207, v98, v207
	v_add_f32_e32 v207, v99, v207
	v_mfma_f32_32x32x16_bf16 v[64:79], v[160:163], v[124:127], v[64:79]
	v_add_f32_e32 v207, v100, v207
	v_add_f32_e32 v207, v101, v207
	v_add_f32_e32 v207, v102, v207
	v_mfma_f32_32x32x16_bf16 v[48:63], v[182:185], v[124:127], v[48:63]
	v_add_f32_e32 v207, v103, v207
	v_add_f32_e32 v207, v104, v207
	v_mfma_f32_32x32x16_bf16 v[32:47], v[198:201], v[124:127], v[32:47]
	v_add_f32_e32 v207, v105, v207
	v_add_f32_e32 v207, v106, v207
	v_add_f32_e32 v207, v107, v207
	v_mfma_f32_32x32x16_bf16 v[16:31], v[202:205], v[124:127], v[16:31]
	v_add_f32_e32 v207, v108, v207
	v_add_f32_e32 v207, v109, v207
	s_add_i32 s6, s10, 0x8000
	s_and_b32 s6, s6, 0x18000
	v_add_u32_e32 v0, s6, v175
	ds_read_b128 v[2:5], v0 offset:0
	ds_read_b128 v[6:9], v0 offset:8192
	v_add_u32_e32 v0, s6, v176
	ds_read_b128 v[10:13], v0 offset:0
	ds_read_b128 v[160:163], v0 offset:8192
	v_add_f32_e32 v207, v110, v207
	v_add_f32_e32 v15, v111, v207
	v_mov_b32_e32 v195, v15
	s_waitcnt lgkmcnt(0)
	v_mfma_f32_32x32x16_bf16 v[112:127], v[2:5], v[144:147], 0
	v_cvt_pk_bf16_f32 v80, v80, v81
	v_cvt_pk_bf16_f32 v81, v82, v83
	v_cvt_pk_bf16_f32 v82, v84, v85
	v_add_u32_e32 v0, s6, v177
	ds_read_b128 v[2:5], v0 offset:0
	v_mfma_f32_32x32x16_bf16 v[128:143], v[6:9], v[144:147], 0
	ds_read_b128 v[6:9], v0 offset:8192
	v_cvt_pk_bf16_f32 v83, v86, v87
	v_cvt_pk_bf16_f32 v84, v88, v89
	v_add_u32_e32 v0, s6, v189
	v_mfma_f32_32x32x16_bf16 v[112:127], v[10:13], v[148:151], v[112:127]
	ds_read_b128 v[10:13], v0 offset:0
	ds_read_b128 v[182:185], v0 offset:8192
	v_cvt_pk_bf16_f32 v85, v90, v91
	v_cvt_pk_bf16_f32 v86, v92, v93
	v_cvt_pk_bf16_f32 v87, v94, v95
	s_waitcnt lgkmcnt(0)
	v_mfma_f32_32x32x16_bf16 v[128:143], v[160:163], v[148:151], v[128:143]
	v_cvt_pk_bf16_f32 v88, v96, v97
	v_cvt_pk_bf16_f32 v89, v98, v99
	v_mfma_f32_32x32x16_bf16 v[112:127], v[2:5], v[152:155], v[112:127]
	v_cvt_pk_bf16_f32 v90, v100, v101
	v_cvt_pk_bf16_f32 v91, v102, v103
	v_cvt_pk_bf16_f32 v92, v104, v105
	v_mfma_f32_32x32x16_bf16 v[128:143], v[6:9], v[152:155], v[128:143]
	v_cvt_pk_bf16_f32 v93, v106, v107
	v_cvt_pk_bf16_f32 v94, v108, v109
	v_mfma_f32_32x32x16_bf16 v[112:127], v[10:13], v[156:159], v[112:127]
	v_cvt_pk_bf16_f32 v95, v110, v111
	s_nop 1
	v_permlane32_swap_b32_e32 v15, v195
	v_mfma_f32_32x32x16_bf16 v[128:143], v[182:185], v[156:159], v[128:143]
	v_permlane32_swap_b32_e32 v80, v82
	v_permlane32_swap_b32_e32 v81, v83
	v_permlane32_swap_b32_e32 v84, v86
	v_permlane32_swap_b32_e32 v85, v87
	v_permlane32_swap_b32_e32 v88, v90
	v_permlane32_swap_b32_e32 v89, v91
	v_permlane32_swap_b32_e32 v92, v94
	v_permlane32_swap_b32_e32 v93, v95
	v_add_f32_e32 v15, v15, v195
	v_fmac_f32_e32 v15, v192, v194
	v_mov_b32_e32 v192, v15
	s_add_i32 s0, s10, 0x0
	s_and_b32 s0, s0, 0x18000
	v_add_u32_e32 v13, s0, v191
	ds_read_b64_tr_b16 v[96:97], v13 offset:0
	ds_read_b64_tr_b16 v[98:99], v13 offset:2048
	ds_read_b64_tr_b16 v[100:101], v13 offset:512
	ds_read_b64_tr_b16 v[102:103], v13 offset:2560
	ds_read_b64_tr_b16 v[104:105], v13 offset:1024
	ds_read_b64_tr_b16 v[106:107], v13 offset:3072
	ds_read_b64_tr_b16 v[108:109], v13 offset:1536
	ds_read_b64_tr_b16 v[110:111], v13 offset:3584
.Lnl_J_e:
.Lnl_qe:
	s_add_i32 s96, s11, 3
	s_cmp_lt_i32 s96, s9
	s_cbranch_scc1 .Lnl_wo
	s_waitcnt vmcnt(0)
	s_branch .Lnl_bo

.Lnl_nors_po:
	ds_read_b64_tr_b16 v[160:161], v13 offset:4096
	ds_read_b64_tr_b16 v[162:163], v13 offset:6144
	ds_read_b64_tr_b16 v[182:183], v13 offset:4608
	ds_read_b64_tr_b16 v[184:185], v13 offset:6656
	ds_read_b64_tr_b16 v[198:199], v13 offset:5120
	ds_read_b64_tr_b16 v[200:201], v13 offset:7168
	ds_read_b64_tr_b16 v[202:203], v13 offset:5632
	ds_read_b64_tr_b16 v[204:205], v13 offset:7680
	s_waitcnt lgkmcnt(8)
	v_mfma_f32_32x32x16_bf16 v[64:79], v[96:99], v[80:83], v[64:79]
	v_mfma_f32_32x32x16_bf16 v[48:63], v[100:103], v[80:83], v[48:63]
	v_mfma_f32_32x32x16_bf16 v[32:47], v[104:107], v[80:83], v[32:47]
	v_mfma_f32_32x32x16_bf16 v[16:31], v[108:111], v[80:83], v[16:31]
	ds_read_b64_tr_b16 v[96:97], v13 offset:8192
	ds_read_b64_tr_b16 v[98:99], v13 offset:10240
	ds_read_b64_tr_b16 v[100:101], v13 offset:8704
	ds_read_b64_tr_b16 v[102:103], v13 offset:10752
	ds_read_b64_tr_b16 v[104:105], v13 offset:9216
	ds_read_b64_tr_b16 v[106:107], v13 offset:11264
	ds_read_b64_tr_b16 v[108:109], v13 offset:9728
	ds_read_b64_tr_b16 v[110:111], v13 offset:11776
	s_waitcnt lgkmcnt(8)
	v_mfma_f32_32x32x16_bf16 v[64:79], v[160:163], v[84:87], v[64:79]
	v_mfma_f32_32x32x16_bf16 v[48:63], v[182:185], v[84:87], v[48:63]
	v_mfma_f32_32x32x16_bf16 v[32:47], v[198:201], v[84:87], v[32:47]
	v_mfma_f32_32x32x16_bf16 v[16:31], v[202:205], v[84:87], v[16:31]
	ds_read_b64_tr_b16 v[160:161], v13 offset:12288
	ds_read_b64_tr_b16 v[162:163], v13 offset:14336
	ds_read_b64_tr_b16 v[182:183], v13 offset:12800
	ds_read_b64_tr_b16 v[184:185], v13 offset:14848
	ds_read_b64_tr_b16 v[198:199], v13 offset:13312
	ds_read_b64_tr_b16 v[200:201], v13 offset:15360
	ds_read_b64_tr_b16 v[202:203], v13 offset:13824
	ds_read_b64_tr_b16 v[204:205], v13 offset:15872
	s_waitcnt lgkmcnt(8)
	v_mfma_f32_32x32x16_bf16 v[64:79], v[96:99], v[88:91], v[64:79]
	v_mfma_f32_32x32x16_bf16 v[48:63], v[100:103], v[88:91], v[48:63]
	v_mfma_f32_32x32x16_bf16 v[32:47], v[104:107], v[88:91], v[32:47]
	v_mfma_f32_32x32x16_bf16 v[16:31], v[108:111], v[88:91], v[16:31]
	s_waitcnt lgkmcnt(0)
	v_mfma_f32_32x32x16_bf16 v[64:79], v[160:163], v[92:95], v[64:79]
	v_mfma_f32_32x32x16_bf16 v[48:63], v[182:185], v[92:95], v[48:63]
	v_mfma_f32_32x32x16_bf16 v[32:47], v[198:201], v[92:95], v[32:47]
	v_mfma_f32_32x32x16_bf16 v[16:31], v[202:205], v[92:95], v[16:31]
	s_add_i32 s0, s10, 0x8000
	s_and_b32 s0, s0, 0x18000
	v_add_u32_e32 v13, s0, v191
	ds_read_b64_tr_b16 v[128:129], v13 offset:0
	ds_read_b64_tr_b16 v[130:131], v13 offset:2048
	ds_read_b64_tr_b16 v[132:133], v13 offset:512
	ds_read_b64_tr_b16 v[134:135], v13 offset:2560
	ds_read_b64_tr_b16 v[136:137], v13 offset:1024
	ds_read_b64_tr_b16 v[138:139], v13 offset:3072
	ds_read_b64_tr_b16 v[140:141], v13 offset:1536
	ds_read_b64_tr_b16 v[142:143], v13 offset:3584
	s_branch .Lnl_qo

.Lnl_nors_ola:
	v_max_f32_e32 v206, v113, v113
	v_max_f32_e32 v207, v112, v112
	v_max_f32_e32 v206, v207, v206
	ds_read_b64_tr_b16 v[160:161], v13 offset:4096
	ds_read_b64_tr_b16 v[162:163], v13 offset:6144
	ds_read_b64_tr_b16 v[182:183], v13 offset:4608
	ds_read_b64_tr_b16 v[184:185], v13 offset:6656
	ds_read_b64_tr_b16 v[198:199], v13 offset:5120
	ds_read_b64_tr_b16 v[200:201], v13 offset:7168
	ds_read_b64_tr_b16 v[202:203], v13 offset:5632
	ds_read_b64_tr_b16 v[204:205], v13 offset:7680
	v_max3_f32 v206, v206, v114, v115
	v_max3_f32 v206, v206, v116, v117
	v_max3_f32 v206, v206, v118, v119
	s_waitcnt lgkmcnt(8)
	v_max3_f32 v206, v206, v120, v121
	v_max3_f32 v206, v206, v122, v123
	v_max3_f32 v206, v206, v124, v125
	v_max3_f32 v206, v206, v126, v127
	v_mfma_f32_32x32x16_bf16 v[64:79], v[96:99], v[80:83], v[64:79]
	v_max3_f32 v206, v206, v128, v129
	v_max3_f32 v206, v206, v130, v131
	v_max3_f32 v206, v206, v132, v133
	v_max3_f32 v206, v206, v134, v135
	v_mfma_f32_32x32x16_bf16 v[48:63], v[100:103], v[80:83], v[48:63]
	v_max3_f32 v206, v206, v136, v137
	v_max3_f32 v206, v206, v138, v139
	v_max3_f32 v206, v206, v140, v141
	v_mfma_f32_32x32x16_bf16 v[32:47], v[104:107], v[80:83], v[32:47]
	v_max3_f32 v206, v206, v142, v143
	v_mov_b32_e32 v207, v206
	s_nop 1
	v_permlane32_swap_b32_e32 v206, v207
	v_mfma_f32_32x32x16_bf16 v[16:31], v[108:111], v[80:83], v[16:31]
	v_max_f32_e32 v207, v207, v207
	v_max_f32_e32 v206, v206, v206
	v_max_f32_e32 v206, v206, v207
	v_sub_f32_e32 v207, v206, v193
	ds_read_b64_tr_b16 v[96:97], v13 offset:8192
	ds_read_b64_tr_b16 v[98:99], v13 offset:10240
	ds_read_b64_tr_b16 v[100:101], v13 offset:8704
	ds_read_b64_tr_b16 v[102:103], v13 offset:10752
	ds_read_b64_tr_b16 v[104:105], v13 offset:9216
	ds_read_b64_tr_b16 v[106:107], v13 offset:11264
	ds_read_b64_tr_b16 v[108:109], v13 offset:9728
	ds_read_b64_tr_b16 v[110:111], v13 offset:11776
	v_cmp_ge_f32_e64 s[0:1], s27, v207
	v_max_f32_e32 v206, v206, v206
	v_max_f32_e32 v207, v193, v193
	v_max_f32_e32 v206, v207, v206
	s_waitcnt lgkmcnt(8)
	s_cmp_eq_u64 s[0:1], exec
	s_cselect_b64 s[0:1], -1, 0
	v_cndmask_b32_e64 v14, v206, v193, s[0:1]
	v_mul_f32_e32 v207, 0xbe38aa3b, v14
	v_mfma_f32_32x32x16_bf16 v[64:79], v[160:163], v[84:87], v[64:79]
	v_fmamk_f32 v174, v112, 0x3e38aa3b, v207
	v_exp_f32_e32 v112, v174
	v_fmamk_f32 v174, v113, 0x3e38aa3b, v207
	v_exp_f32_e32 v113, v174
	v_mfma_f32_32x32x16_bf16 v[48:63], v[182:185], v[84:87], v[48:63]
	v_fmamk_f32 v174, v114, 0x3e38aa3b, v207
	v_exp_f32_e32 v114, v174
	v_fmamk_f32 v174, v115, 0x3e38aa3b, v207
	v_exp_f32_e32 v115, v174
	v_mfma_f32_32x32x16_bf16 v[32:47], v[198:201], v[84:87], v[32:47]
	v_fmamk_f32 v174, v116, 0x3e38aa3b, v207
	v_exp_f32_e32 v116, v174
	v_fmamk_f32 v174, v117, 0x3e38aa3b, v207
	v_exp_f32_e32 v117, v174
	v_mfma_f32_32x32x16_bf16 v[16:31], v[202:205], v[84:87], v[16:31]
	v_fmamk_f32 v174, v118, 0x3e38aa3b, v207
	v_exp_f32_e32 v118, v174
	v_fmamk_f32 v174, v119, 0x3e38aa3b, v207
	ds_read_b64_tr_b16 v[160:161], v13 offset:12288
	ds_read_b64_tr_b16 v[162:163], v13 offset:14336
	ds_read_b64_tr_b16 v[182:183], v13 offset:12800
	ds_read_b64_tr_b16 v[184:185], v13 offset:14848
	ds_read_b64_tr_b16 v[198:199], v13 offset:13312
	ds_read_b64_tr_b16 v[200:201], v13 offset:15360
	ds_read_b64_tr_b16 v[202:203], v13 offset:13824
	ds_read_b64_tr_b16 v[204:205], v13 offset:15872
	v_exp_f32_e32 v119, v174
	v_fmamk_f32 v174, v120, 0x3e38aa3b, v207
	v_exp_f32_e32 v120, v174
	v_fmamk_f32 v174, v121, 0x3e38aa3b, v207
	s_waitcnt lgkmcnt(8)
	v_exp_f32_e32 v121, v174
	v_fmamk_f32 v174, v122, 0x3e38aa3b, v207
	v_exp_f32_e32 v122, v174
	v_fmamk_f32 v174, v123, 0x3e38aa3b, v207
	v_mfma_f32_32x32x16_bf16 v[64:79], v[96:99], v[88:91], v[64:79]
	v_exp_f32_e32 v123, v174
	v_fmamk_f32 v174, v124, 0x3e38aa3b, v207
	v_exp_f32_e32 v124, v174
	v_fmamk_f32 v174, v125, 0x3e38aa3b, v207
	v_mfma_f32_32x32x16_bf16 v[48:63], v[100:103], v[88:91], v[48:63]
	v_exp_f32_e32 v125, v174
	v_fmamk_f32 v174, v126, 0x3e38aa3b, v207
	v_exp_f32_e32 v126, v174
	v_mfma_f32_32x32x16_bf16 v[32:47], v[104:107], v[88:91], v[32:47]
	v_fmamk_f32 v174, v127, 0x3e38aa3b, v207
	v_exp_f32_e32 v127, v174
	v_fmamk_f32 v174, v128, 0x3e38aa3b, v207
	v_exp_f32_e32 v128, v174
	v_mfma_f32_32x32x16_bf16 v[16:31], v[108:111], v[88:91], v[16:31]
	v_fmamk_f32 v174, v129, 0x3e38aa3b, v207
	v_exp_f32_e32 v129, v174
	v_fmamk_f32 v174, v130, 0x3e38aa3b, v207
	v_exp_f32_e32 v130, v174
	s_waitcnt lgkmcnt(0)
	v_fmamk_f32 v174, v131, 0x3e38aa3b, v207
	v_exp_f32_e32 v131, v174
	v_fmamk_f32 v174, v132, 0x3e38aa3b, v207
	v_exp_f32_e32 v132, v174
	v_mfma_f32_32x32x16_bf16 v[64:79], v[160:163], v[92:95], v[64:79]
	v_fmamk_f32 v174, v133, 0x3e38aa3b, v207
	v_exp_f32_e32 v133, v174
	v_fmamk_f32 v174, v134, 0x3e38aa3b, v207
	v_mfma_f32_32x32x16_bf16 v[48:63], v[182:185], v[92:95], v[48:63]
	v_exp_f32_e32 v134, v174
	v_fmamk_f32 v174, v135, 0x3e38aa3b, v207
	v_exp_f32_e32 v135, v174
	v_fmamk_f32 v174, v136, 0x3e38aa3b, v207
	v_mfma_f32_32x32x16_bf16 v[32:47], v[198:201], v[92:95], v[32:47]
	v_exp_f32_e32 v136, v174
	v_fmamk_f32 v174, v137, 0x3e38aa3b, v207
	v_exp_f32_e32 v137, v174
	v_fmamk_f32 v174, v138, 0x3e38aa3b, v207
	v_mfma_f32_32x32x16_bf16 v[16:31], v[202:205], v[92:95], v[16:31]
	v_exp_f32_e32 v138, v174
	v_fmamk_f32 v174, v139, 0x3e38aa3b, v207
	v_exp_f32_e32 v139, v174
	v_fmamk_f32 v174, v140, 0x3e38aa3b, v207
	v_exp_f32_e32 v140, v174
	v_fmamk_f32 v174, v141, 0x3e38aa3b, v207
	v_exp_f32_e32 v141, v174
	v_fmamk_f32 v174, v142, 0x3e38aa3b, v207
	v_exp_f32_e32 v142, v174
	v_fmamk_f32 v174, v143, 0x3e38aa3b, v207
	v_exp_f32_e32 v143, v174
	v_sub_f32_e32 v206, v193, v206
	v_mul_f32_e32 v206, 0x3e38aa3b, v206
	v_exp_f32_e32 v206, v206
	v_add_f32_e32 v207, 0, v112
	v_cndmask_b32_e64 v194, v206, 1.0, s[0:1]
	v_mov_b32_e32 v193, v14
	v_add_f32_e32 v207, v113, v207
	v_add_f32_e32 v207, v114, v207
	v_add_f32_e32 v207, v115, v207
	v_add_f32_e32 v207, v116, v207
	v_add_f32_e32 v207, v117, v207
	v_add_f32_e32 v207, v118, v207
	v_add_f32_e32 v207, v119, v207
	v_add_f32_e32 v207, v120, v207
	v_add_f32_e32 v207, v121, v207
	v_add_f32_e32 v207, v122, v207
	v_add_f32_e32 v207, v123, v207
	v_add_f32_e32 v207, v124, v207
	v_add_f32_e32 v207, v125, v207
	v_add_f32_e32 v207, v126, v207
	v_add_f32_e32 v207, v127, v207
	v_add_f32_e32 v207, v128, v207
	v_add_f32_e32 v207, v129, v207
	v_add_f32_e32 v207, v130, v207
	v_add_f32_e32 v207, v131, v207
	v_add_f32_e32 v207, v132, v207
	v_add_f32_e32 v207, v133, v207
	v_add_f32_e32 v207, v134, v207
	v_add_f32_e32 v207, v135, v207
	v_add_f32_e32 v207, v136, v207
	v_add_f32_e32 v207, v137, v207
	v_add_f32_e32 v207, v138, v207
	v_add_f32_e32 v207, v139, v207
	v_add_f32_e32 v207, v140, v207
	v_add_f32_e32 v207, v141, v207
	v_add_f32_e32 v207, v142, v207
	v_add_f32_e32 v15, v143, v207
	v_mov_b32_e32 v195, v15
	v_cvt_pk_bf16_f32 v112, v112, v113
	v_cvt_pk_bf16_f32 v113, v114, v115
	v_cvt_pk_bf16_f32 v114, v116, v117
	v_cvt_pk_bf16_f32 v115, v118, v119
	v_cvt_pk_bf16_f32 v116, v120, v121
	v_cvt_pk_bf16_f32 v117, v122, v123
	v_cvt_pk_bf16_f32 v118, v124, v125
	v_cvt_pk_bf16_f32 v119, v126, v127
	v_cvt_pk_bf16_f32 v120, v128, v129
	v_cvt_pk_bf16_f32 v121, v130, v131
	v_cvt_pk_bf16_f32 v122, v132, v133
	v_cvt_pk_bf16_f32 v123, v134, v135
	v_cvt_pk_bf16_f32 v124, v136, v137
	v_cvt_pk_bf16_f32 v125, v138, v139
	v_cvt_pk_bf16_f32 v126, v140, v141
	v_cvt_pk_bf16_f32 v127, v142, v143
	s_nop 1
	v_permlane32_swap_b32_e32 v15, v195
	v_permlane32_swap_b32_e32 v112, v114
	v_permlane32_swap_b32_e32 v113, v115
	v_permlane32_swap_b32_e32 v116, v118
	v_permlane32_swap_b32_e32 v117, v119
	v_permlane32_swap_b32_e32 v120, v122
	v_permlane32_swap_b32_e32 v121, v123
	v_permlane32_swap_b32_e32 v124, v126
	v_permlane32_swap_b32_e32 v125, v127
	v_add_f32_e32 v15, v15, v195
	v_fmac_f32_e32 v15, v192, v194
	v_mov_b32_e32 v192, v15
	s_add_i32 s0, s10, 0x8000
	s_and_b32 s0, s0, 0x18000
	v_add_u32_e32 v13, s0, v191
	ds_read_b64_tr_b16 v[128:129], v13 offset:0
	ds_read_b64_tr_b16 v[130:131], v13 offset:2048
	ds_read_b64_tr_b16 v[132:133], v13 offset:512
	ds_read_b64_tr_b16 v[134:135], v13 offset:2560
	ds_read_b64_tr_b16 v[136:137], v13 offset:1024
	ds_read_b64_tr_b16 v[138:139], v13 offset:3072
	ds_read_b64_tr_b16 v[140:141], v13 offset:1536
	ds_read_b64_tr_b16 v[142:143], v13 offset:3584
	s_branch .Lnl_J_ol

.Lnl_nors_olb:
	v_max_f32_e32 v206, v113, v113
	v_max_f32_e32 v207, v112, v112
	v_max_f32_e32 v206, v207, v206
	v_max3_f32 v206, v206, v114, v115
	v_max3_f32 v206, v206, v116, v117
	v_max3_f32 v206, v206, v118, v119
	v_max3_f32 v206, v206, v120, v121
	v_max3_f32 v206, v206, v122, v123
	v_max3_f32 v206, v206, v124, v125
	v_max3_f32 v206, v206, v126, v127
	v_max3_f32 v206, v206, v128, v129
	v_max3_f32 v206, v206, v130, v131
	v_max3_f32 v206, v206, v132, v133
	v_max3_f32 v206, v206, v134, v135
	v_max3_f32 v206, v206, v136, v137
	v_max3_f32 v206, v206, v138, v139
	v_max3_f32 v206, v206, v140, v141
	v_max3_f32 v206, v206, v142, v143
	v_mov_b32_e32 v207, v206
	s_nop 1
	v_permlane32_swap_b32_e32 v206, v207
	v_max_f32_e32 v207, v207, v207
	v_max_f32_e32 v206, v206, v206
	v_max_f32_e32 v206, v206, v207
	v_sub_f32_e32 v207, v206, v193
	v_cmp_ge_f32_e64 s[0:1], s27, v207
	v_max_f32_e32 v206, v206, v206
	v_max_f32_e32 v207, v193, v193
	v_max_f32_e32 v206, v207, v206
	s_cmp_eq_u64 s[0:1], exec
	s_cselect_b64 s[0:1], -1, 0
	v_cndmask_b32_e64 v14, v206, v193, s[0:1]
	v_mul_f32_e32 v207, 0xbe38aa3b, v14
	v_fmamk_f32 v174, v112, 0x3e38aa3b, v207
	v_exp_f32_e32 v112, v174
	v_fmamk_f32 v174, v113, 0x3e38aa3b, v207
	v_exp_f32_e32 v113, v174
	v_fmamk_f32 v174, v114, 0x3e38aa3b, v207
	v_exp_f32_e32 v114, v174
	v_fmamk_f32 v174, v115, 0x3e38aa3b, v207
	v_exp_f32_e32 v115, v174
	v_fmamk_f32 v174, v116, 0x3e38aa3b, v207
	v_exp_f32_e32 v116, v174
	v_fmamk_f32 v174, v117, 0x3e38aa3b, v207
	v_exp_f32_e32 v117, v174
	v_fmamk_f32 v174, v118, 0x3e38aa3b, v207
	v_exp_f32_e32 v118, v174
	v_fmamk_f32 v174, v119, 0x3e38aa3b, v207
	v_exp_f32_e32 v119, v174
	v_fmamk_f32 v174, v120, 0x3e38aa3b, v207
	v_exp_f32_e32 v120, v174
	v_fmamk_f32 v174, v121, 0x3e38aa3b, v207
	v_exp_f32_e32 v121, v174
	v_fmamk_f32 v174, v122, 0x3e38aa3b, v207
	v_exp_f32_e32 v122, v174
	v_fmamk_f32 v174, v123, 0x3e38aa3b, v207
	v_exp_f32_e32 v123, v174
	v_fmamk_f32 v174, v124, 0x3e38aa3b, v207
	v_exp_f32_e32 v124, v174
	v_fmamk_f32 v174, v125, 0x3e38aa3b, v207
	v_exp_f32_e32 v125, v174
	v_fmamk_f32 v174, v126, 0x3e38aa3b, v207
	v_exp_f32_e32 v126, v174
	v_fmamk_f32 v174, v127, 0x3e38aa3b, v207
	v_exp_f32_e32 v127, v174
	v_fmamk_f32 v174, v128, 0x3e38aa3b, v207
	v_exp_f32_e32 v128, v174
	v_fmamk_f32 v174, v129, 0x3e38aa3b, v207
	v_exp_f32_e32 v129, v174
	v_fmamk_f32 v174, v130, 0x3e38aa3b, v207
	v_exp_f32_e32 v130, v174
	v_fmamk_f32 v174, v131, 0x3e38aa3b, v207
	v_exp_f32_e32 v131, v174
	v_fmamk_f32 v174, v132, 0x3e38aa3b, v207
	ds_read_b64_tr_b16 v[160:161], v13 offset:4096
	ds_read_b64_tr_b16 v[162:163], v13 offset:6144
	ds_read_b64_tr_b16 v[182:183], v13 offset:4608
	ds_read_b64_tr_b16 v[184:185], v13 offset:6656
	ds_read_b64_tr_b16 v[198:199], v13 offset:5120
	ds_read_b64_tr_b16 v[200:201], v13 offset:7168
	ds_read_b64_tr_b16 v[202:203], v13 offset:5632
	ds_read_b64_tr_b16 v[204:205], v13 offset:7680
	v_exp_f32_e32 v132, v174
	v_fmamk_f32 v174, v133, 0x3e38aa3b, v207
	v_exp_f32_e32 v133, v174
	s_waitcnt lgkmcnt(8)
	v_fmamk_f32 v174, v134, 0x3e38aa3b, v207
	v_exp_f32_e32 v134, v174
	v_fmamk_f32 v174, v135, 0x3e38aa3b, v207
	v_exp_f32_e32 v135, v174
	v_mfma_f32_32x32x16_bf16 v[64:79], v[96:99], v[80:83], v[64:79]
	v_fmamk_f32 v174, v136, 0x3e38aa3b, v207
	v_exp_f32_e32 v136, v174
	v_fmamk_f32 v174, v137, 0x3e38aa3b, v207
	v_mfma_f32_32x32x16_bf16 v[48:63], v[100:103], v[80:83], v[48:63]
	v_exp_f32_e32 v137, v174
	v_fmamk_f32 v174, v138, 0x3e38aa3b, v207
	v_exp_f32_e32 v138, v174
	v_fmamk_f32 v174, v139, 0x3e38aa3b, v207
	v_mfma_f32_32x32x16_bf16 v[32:47], v[104:107], v[80:83], v[32:47]
	v_exp_f32_e32 v139, v174
	v_fmamk_f32 v174, v140, 0x3e38aa3b, v207
	v_exp_f32_e32 v140, v174
	v_mfma_f32_32x32x16_bf16 v[16:31], v[108:111], v[80:83], v[16:31]
	v_fmamk_f32 v174, v141, 0x3e38aa3b, v207
	v_exp_f32_e32 v141, v174
	v_fmamk_f32 v174, v142, 0x3e38aa3b, v207
	v_exp_f32_e32 v142, v174
	ds_read_b64_tr_b16 v[96:97], v13 offset:8192
	ds_read_b64_tr_b16 v[98:99], v13 offset:10240
	ds_read_b64_tr_b16 v[100:101], v13 offset:8704
	ds_read_b64_tr_b16 v[102:103], v13 offset:10752
	ds_read_b64_tr_b16 v[104:105], v13 offset:9216
	ds_read_b64_tr_b16 v[106:107], v13 offset:11264
	ds_read_b64_tr_b16 v[108:109], v13 offset:9728
	ds_read_b64_tr_b16 v[110:111], v13 offset:11776
	v_fmamk_f32 v174, v143, 0x3e38aa3b, v207
	v_exp_f32_e32 v143, v174
	v_sub_f32_e32 v206, v193, v206
	s_waitcnt lgkmcnt(8)
	v_mul_f32_e32 v206, 0x3e38aa3b, v206
	v_exp_f32_e32 v206, v206
	v_add_f32_e32 v207, 0, v112
	v_cndmask_b32_e64 v194, v206, 1.0, s[0:1]
	v_mfma_f32_32x32x16_bf16 v[64:79], v[160:163], v[84:87], v[64:79]
	v_mov_b32_e32 v193, v14
	v_add_f32_e32 v207, v113, v207
	v_add_f32_e32 v207, v114, v207
	v_add_f32_e32 v207, v115, v207
	v_mfma_f32_32x32x16_bf16 v[48:63], v[182:185], v[84:87], v[48:63]
	v_add_f32_e32 v207, v116, v207
	v_add_f32_e32 v207, v117, v207
	v_add_f32_e32 v207, v118, v207
	v_mfma_f32_32x32x16_bf16 v[32:47], v[198:201], v[84:87], v[32:47]
	v_add_f32_e32 v207, v119, v207
	v_add_f32_e32 v207, v120, v207
	v_add_f32_e32 v207, v121, v207
	v_add_f32_e32 v207, v122, v207
	v_mfma_f32_32x32x16_bf16 v[16:31], v[202:205], v[84:87], v[16:31]
	v_add_f32_e32 v207, v123, v207
	v_add_f32_e32 v207, v124, v207
	v_add_f32_e32 v207, v125, v207
	ds_read_b64_tr_b16 v[160:161], v13 offset:12288
	ds_read_b64_tr_b16 v[162:163], v13 offset:14336
	ds_read_b64_tr_b16 v[182:183], v13 offset:12800
	ds_read_b64_tr_b16 v[184:185], v13 offset:14848
	ds_read_b64_tr_b16 v[198:199], v13 offset:13312
	ds_read_b64_tr_b16 v[200:201], v13 offset:15360
	ds_read_b64_tr_b16 v[202:203], v13 offset:13824
	ds_read_b64_tr_b16 v[204:205], v13 offset:15872
	v_add_f32_e32 v207, v126, v207
	v_add_f32_e32 v207, v127, v207
	v_add_f32_e32 v207, v128, v207
	v_add_f32_e32 v207, v129, v207
	s_waitcnt lgkmcnt(8)
	v_add_f32_e32 v207, v130, v207
	v_add_f32_e32 v207, v131, v207
	v_add_f32_e32 v207, v132, v207
	v_mfma_f32_32x32x16_bf16 v[64:79], v[96:99], v[88:91], v[64:79]
	v_add_f32_e32 v207, v133, v207
	v_add_f32_e32 v207, v134, v207
	v_add_f32_e32 v207, v135, v207
	v_add_f32_e32 v207, v136, v207
	v_mfma_f32_32x32x16_bf16 v[48:63], v[100:103], v[88:91], v[48:63]
	v_add_f32_e32 v207, v137, v207
	v_add_f32_e32 v207, v138, v207
	v_add_f32_e32 v207, v139, v207
	v_add_f32_e32 v207, v140, v207
	v_mfma_f32_32x32x16_bf16 v[32:47], v[104:107], v[88:91], v[32:47]
	v_add_f32_e32 v207, v141, v207
	v_add_f32_e32 v207, v142, v207
	v_add_f32_e32 v15, v143, v207
	v_mfma_f32_32x32x16_bf16 v[16:31], v[108:111], v[88:91], v[16:31]
	v_mov_b32_e32 v195, v15
	v_cvt_pk_bf16_f32 v112, v112, v113
	v_cvt_pk_bf16_f32 v113, v114, v115
	v_cvt_pk_bf16_f32 v114, v116, v117
	s_waitcnt lgkmcnt(0)
	v_cvt_pk_bf16_f32 v115, v118, v119
	v_cvt_pk_bf16_f32 v116, v120, v121
	v_cvt_pk_bf16_f32 v117, v122, v123
	v_mfma_f32_32x32x16_bf16 v[64:79], v[160:163], v[92:95], v[64:79]
	v_cvt_pk_bf16_f32 v118, v124, v125
	v_cvt_pk_bf16_f32 v119, v126, v127
	v_cvt_pk_bf16_f32 v120, v128, v129
	v_cvt_pk_bf16_f32 v121, v130, v131
	v_mfma_f32_32x32x16_bf16 v[48:63], v[182:185], v[92:95], v[48:63]
	v_cvt_pk_bf16_f32 v122, v132, v133
	v_cvt_pk_bf16_f32 v123, v134, v135
	v_cvt_pk_bf16_f32 v124, v136, v137
	v_mfma_f32_32x32x16_bf16 v[32:47], v[198:201], v[92:95], v[32:47]
	v_cvt_pk_bf16_f32 v125, v138, v139
	v_cvt_pk_bf16_f32 v126, v140, v141
	v_cvt_pk_bf16_f32 v127, v142, v143
	s_nop 1
	v_mfma_f32_32x32x16_bf16 v[16:31], v[202:205], v[92:95], v[16:31]
	v_permlane32_swap_b32_e32 v15, v195
	v_permlane32_swap_b32_e32 v112, v114
	v_permlane32_swap_b32_e32 v113, v115
	v_permlane32_swap_b32_e32 v116, v118
	v_permlane32_swap_b32_e32 v117, v119
	v_permlane32_swap_b32_e32 v120, v122
	v_permlane32_swap_b32_e32 v121, v123
	v_permlane32_swap_b32_e32 v124, v126
	v_permlane32_swap_b32_e32 v125, v127
	v_add_f32_e32 v15, v15, v195
	v_fmac_f32_e32 v15, v192, v194
	v_mov_b32_e32 v192, v15
	s_add_i32 s0, s10, 0x8000
	s_and_b32 s0, s0, 0x18000
	v_add_u32_e32 v13, s0, v191
	ds_read_b64_tr_b16 v[128:129], v13 offset:0
	ds_read_b64_tr_b16 v[130:131], v13 offset:2048
	ds_read_b64_tr_b16 v[132:133], v13 offset:512
	ds_read_b64_tr_b16 v[134:135], v13 offset:2560
	ds_read_b64_tr_b16 v[136:137], v13 offset:1024
	ds_read_b64_tr_b16 v[138:139], v13 offset:3072
	ds_read_b64_tr_b16 v[140:141], v13 offset:1536
	ds_read_b64_tr_b16 v[142:143], v13 offset:3584
.Lnl_J_ol:
	s_branch .Lnl_qo

.Lnl_nors_oa:
	v_max_f32_e32 v206, v113, v113
	v_max_f32_e32 v207, v112, v112
	v_max_f32_e32 v206, v207, v206
	ds_read_b64_tr_b16 v[160:161], v13 offset:4096
	ds_read_b64_tr_b16 v[162:163], v13 offset:6144
	ds_read_b64_tr_b16 v[182:183], v13 offset:4608
	ds_read_b64_tr_b16 v[184:185], v13 offset:6656
	ds_read_b64_tr_b16 v[198:199], v13 offset:5120
	ds_read_b64_tr_b16 v[200:201], v13 offset:7168
	ds_read_b64_tr_b16 v[202:203], v13 offset:5632
	ds_read_b64_tr_b16 v[204:205], v13 offset:7680
	v_max3_f32 v206, v206, v114, v115
	v_max3_f32 v206, v206, v116, v117
	s_waitcnt lgkmcnt(8)
	v_max3_f32 v206, v206, v118, v119
	v_max3_f32 v206, v206, v120, v121
	v_max3_f32 v206, v206, v122, v123
	v_mfma_f32_32x32x16_bf16 v[64:79], v[96:99], v[80:83], v[64:79]
	v_max3_f32 v206, v206, v124, v125
	v_max3_f32 v206, v206, v126, v127
	v_max3_f32 v206, v206, v128, v129
	v_mfma_f32_32x32x16_bf16 v[48:63], v[100:103], v[80:83], v[48:63]
	v_max3_f32 v206, v206, v130, v131
	v_max3_f32 v206, v206, v132, v133
	v_mfma_f32_32x32x16_bf16 v[32:47], v[104:107], v[80:83], v[32:47]
	v_max3_f32 v206, v206, v134, v135
	v_max3_f32 v206, v206, v136, v137
	v_max3_f32 v206, v206, v138, v139
	v_mfma_f32_32x32x16_bf16 v[16:31], v[108:111], v[80:83], v[16:31]
	v_max3_f32 v206, v206, v140, v141
	v_max3_f32 v206, v206, v142, v143
	v_mov_b32_e32 v207, v206
	ds_read_b64_tr_b16 v[96:97], v13 offset:8192
	ds_read_b64_tr_b16 v[98:99], v13 offset:10240
	ds_read_b64_tr_b16 v[100:101], v13 offset:8704
	ds_read_b64_tr_b16 v[102:103], v13 offset:10752
	ds_read_b64_tr_b16 v[104:105], v13 offset:9216
	ds_read_b64_tr_b16 v[106:107], v13 offset:11264
	ds_read_b64_tr_b16 v[108:109], v13 offset:9728
	ds_read_b64_tr_b16 v[110:111], v13 offset:11776
	s_nop 1
	v_permlane32_swap_b32_e32 v206, v207
	s_waitcnt lgkmcnt(8)
	v_max_f32_e32 v207, v207, v207
	v_max_f32_e32 v206, v206, v206
	v_max_f32_e32 v206, v206, v207
	v_mfma_f32_32x32x16_bf16 v[64:79], v[160:163], v[84:87], v[64:79]
	v_sub_f32_e32 v207, v206, v193
	v_cmp_ge_f32_e64 s[0:1], s27, v207
	v_max_f32_e32 v206, v206, v206
	v_mfma_f32_32x32x16_bf16 v[48:63], v[182:185], v[84:87], v[48:63]
	v_max_f32_e32 v207, v193, v193
	v_max_f32_e32 v206, v207, v206
	v_mfma_f32_32x32x16_bf16 v[32:47], v[198:201], v[84:87], v[32:47]
	s_cmp_eq_u64 s[0:1], exec
	s_cselect_b64 s[0:1], -1, 0
	v_cndmask_b32_e64 v14, v206, v193, s[0:1]
	v_mul_f32_e32 v207, 0xbe38aa3b, v14
	v_mfma_f32_32x32x16_bf16 v[16:31], v[202:205], v[84:87], v[16:31]
	v_fmamk_f32 v174, v112, 0x3e38aa3b, v207
	v_exp_f32_e32 v112, v174
	v_fmamk_f32 v174, v113, 0x3e38aa3b, v207
	ds_read_b64_tr_b16 v[160:161], v13 offset:12288
	ds_read_b64_tr_b16 v[162:163], v13 offset:14336
	ds_read_b64_tr_b16 v[182:183], v13 offset:12800
	ds_read_b64_tr_b16 v[184:185], v13 offset:14848
	ds_read_b64_tr_b16 v[198:199], v13 offset:13312
	ds_read_b64_tr_b16 v[200:201], v13 offset:15360
	ds_read_b64_tr_b16 v[202:203], v13 offset:13824
	ds_read_b64_tr_b16 v[204:205], v13 offset:15872
	v_exp_f32_e32 v113, v174
	v_fmamk_f32 v174, v114, 0x3e38aa3b, v207
	s_waitcnt lgkmcnt(8)
	v_exp_f32_e32 v114, v174
	v_fmamk_f32 v174, v115, 0x3e38aa3b, v207
	v_exp_f32_e32 v115, v174
	v_mfma_f32_32x32x16_bf16 v[64:79], v[96:99], v[88:91], v[64:79]
	v_fmamk_f32 v174, v116, 0x3e38aa3b, v207
	v_exp_f32_e32 v116, v174
	v_fmamk_f32 v174, v117, 0x3e38aa3b, v207
	v_mfma_f32_32x32x16_bf16 v[48:63], v[100:103], v[88:91], v[48:63]
	v_exp_f32_e32 v117, v174
	v_fmamk_f32 v174, v118, 0x3e38aa3b, v207
	v_exp_f32_e32 v118, v174
	v_mfma_f32_32x32x16_bf16 v[32:47], v[104:107], v[88:91], v[32:47]
	v_fmamk_f32 v174, v119, 0x3e38aa3b, v207
	v_exp_f32_e32 v119, v174
	v_mfma_f32_32x32x16_bf16 v[16:31], v[108:111], v[88:91], v[16:31]
	v_fmamk_f32 v174, v120, 0x3e38aa3b, v207
	v_exp_f32_e32 v120, v174
	v_fmamk_f32 v174, v121, 0x3e38aa3b, v207
	s_waitcnt lgkmcnt(0)
	v_exp_f32_e32 v121, v174
	v_fmamk_f32 v174, v122, 0x3e38aa3b, v207
	v_exp_f32_e32 v122, v174
	v_mfma_f32_32x32x16_bf16 v[64:79], v[160:163], v[92:95], v[64:79]
	v_fmamk_f32 v174, v123, 0x3e38aa3b, v207
	v_exp_f32_e32 v123, v174
	v_mfma_f32_32x32x16_bf16 v[48:63], v[182:185], v[92:95], v[48:63]
	v_fmamk_f32 v174, v124, 0x3e38aa3b, v207
	v_exp_f32_e32 v124, v174
	v_fmamk_f32 v174, v125, 0x3e38aa3b, v207
	v_mfma_f32_32x32x16_bf16 v[32:47], v[198:201], v[92:95], v[32:47]
	v_exp_f32_e32 v125, v174
	v_fmamk_f32 v174, v126, 0x3e38aa3b, v207
	v_exp_f32_e32 v126, v174
	v_mfma_f32_32x32x16_bf16 v[16:31], v[202:205], v[92:95], v[16:31]
	v_fmamk_f32 v174, v127, 0x3e38aa3b, v207
	v_exp_f32_e32 v127, v174
	s_add_i32 s6, s10, 0x10000
	s_and_b32 s6, s6, 0x18000
	v_add_u32_e32 v0, s6, v175
	ds_read_b128 v[2:5], v0 offset:0
	ds_read_b128 v[6:9], v0 offset:8192
	v_add_u32_e32 v0, s6, v176
	ds_read_b128 v[10:13], v0 offset:0
	ds_read_b128 v[160:163], v0 offset:8192
	v_fmamk_f32 v174, v128, 0x3e38aa3b, v207
	v_exp_f32_e32 v128, v174
	v_fmamk_f32 v174, v129, 0x3e38aa3b, v207
	s_waitcnt lgkmcnt(0)
	v_mfma_f32_32x32x16_bf16 v[80:95], v[2:5], v[144:147], 0
	v_exp_f32_e32 v129, v174
	v_fmamk_f32 v174, v130, 0x3e38aa3b, v207
	v_exp_f32_e32 v130, v174
	v_add_u32_e32 v0, s6, v177
	ds_read_b128 v[2:5], v0 offset:0
	v_mfma_f32_32x32x16_bf16 v[96:111], v[6:9], v[144:147], 0
	ds_read_b128 v[6:9], v0 offset:8192
	v_fmamk_f32 v174, v131, 0x3e38aa3b, v207
	v_exp_f32_e32 v131, v174
	v_add_u32_e32 v0, s6, v189
	v_mfma_f32_32x32x16_bf16 v[80:95], v[10:13], v[148:151], v[80:95]
	ds_read_b128 v[10:13], v0 offset:0
	ds_read_b128 v[182:185], v0 offset:8192
	v_fmamk_f32 v174, v132, 0x3e38aa3b, v207
	v_exp_f32_e32 v132, v174
	v_fmamk_f32 v174, v133, 0x3e38aa3b, v207
	s_waitcnt lgkmcnt(0)
	v_mfma_f32_32x32x16_bf16 v[96:111], v[160:163], v[148:151], v[96:111]
	v_exp_f32_e32 v133, v174
	v_fmamk_f32 v174, v134, 0x3e38aa3b, v207
	v_exp_f32_e32 v134, v174
	v_mfma_f32_32x32x16_bf16 v[80:95], v[2:5], v[152:155], v[80:95]
	v_fmamk_f32 v174, v135, 0x3e38aa3b, v207
	v_exp_f32_e32 v135, v174
	v_mfma_f32_32x32x16_bf16 v[96:111], v[6:9], v[152:155], v[96:111]
	v_fmamk_f32 v174, v136, 0x3e38aa3b, v207
	v_exp_f32_e32 v136, v174
	v_fmamk_f32 v174, v137, 0x3e38aa3b, v207
	v_mfma_f32_32x32x16_bf16 v[80:95], v[10:13], v[156:159], v[80:95]
	v_exp_f32_e32 v137, v174
	v_fmamk_f32 v174, v138, 0x3e38aa3b, v207
	v_exp_f32_e32 v138, v174
	v_mfma_f32_32x32x16_bf16 v[96:111], v[182:185], v[156:159], v[96:111]
	v_fmamk_f32 v174, v139, 0x3e38aa3b, v207
	v_exp_f32_e32 v139, v174
	v_fmamk_f32 v174, v140, 0x3e38aa3b, v207
	v_exp_f32_e32 v140, v174
	v_fmamk_f32 v174, v141, 0x3e38aa3b, v207
	v_exp_f32_e32 v141, v174
	v_fmamk_f32 v174, v142, 0x3e38aa3b, v207
	v_exp_f32_e32 v142, v174
	v_fmamk_f32 v174, v143, 0x3e38aa3b, v207
	v_exp_f32_e32 v143, v174
	v_sub_f32_e32 v206, v193, v206
	v_mul_f32_e32 v206, 0x3e38aa3b, v206
	v_exp_f32_e32 v206, v206
	v_add_f32_e32 v207, 0, v112
	v_cndmask_b32_e64 v194, v206, 1.0, s[0:1]
	v_mov_b32_e32 v193, v14
	v_add_f32_e32 v207, v113, v207
	v_add_f32_e32 v207, v114, v207
	v_add_f32_e32 v207, v115, v207
	v_add_f32_e32 v207, v116, v207
	v_add_f32_e32 v207, v117, v207
	v_add_f32_e32 v207, v118, v207
	v_add_f32_e32 v207, v119, v207
	v_add_f32_e32 v207, v120, v207
	v_add_f32_e32 v207, v121, v207
	v_add_f32_e32 v207, v122, v207
	v_add_f32_e32 v207, v123, v207
	v_add_f32_e32 v207, v124, v207
	v_add_f32_e32 v207, v125, v207
	v_add_f32_e32 v207, v126, v207
	v_add_f32_e32 v207, v127, v207
	v_add_f32_e32 v207, v128, v207
	v_add_f32_e32 v207, v129, v207
	v_add_f32_e32 v207, v130, v207
	v_add_f32_e32 v207, v131, v207
	v_add_f32_e32 v207, v132, v207
	v_add_f32_e32 v207, v133, v207
	v_add_f32_e32 v207, v134, v207
	v_add_f32_e32 v207, v135, v207
	v_add_f32_e32 v207, v136, v207
	v_add_f32_e32 v207, v137, v207
	v_add_f32_e32 v207, v138, v207
	v_add_f32_e32 v207, v139, v207
	v_add_f32_e32 v207, v140, v207
	v_add_f32_e32 v207, v141, v207
	v_add_f32_e32 v207, v142, v207
	v_add_f32_e32 v15, v143, v207
	v_mov_b32_e32 v195, v15
	v_cvt_pk_bf16_f32 v112, v112, v113
	v_cvt_pk_bf16_f32 v113, v114, v115
	v_cvt_pk_bf16_f32 v114, v116, v117
	v_cvt_pk_bf16_f32 v115, v118, v119
	v_cvt_pk_bf16_f32 v116, v120, v121
	v_cvt_pk_bf16_f32 v117, v122, v123
	v_cvt_pk_bf16_f32 v118, v124, v125
	v_cvt_pk_bf16_f32 v119, v126, v127
	v_cvt_pk_bf16_f32 v120, v128, v129
	v_cvt_pk_bf16_f32 v121, v130, v131
	v_cvt_pk_bf16_f32 v122, v132, v133
	v_cvt_pk_bf16_f32 v123, v134, v135
	v_cvt_pk_bf16_f32 v124, v136, v137
	v_cvt_pk_bf16_f32 v125, v138, v139
	v_cvt_pk_bf16_f32 v126, v140, v141
	v_cvt_pk_bf16_f32 v127, v142, v143
	s_nop 1
	v_permlane32_swap_b32_e32 v15, v195
	v_permlane32_swap_b32_e32 v112, v114
	v_permlane32_swap_b32_e32 v113, v115
	v_permlane32_swap_b32_e32 v116, v118
	v_permlane32_swap_b32_e32 v117, v119
	v_permlane32_swap_b32_e32 v120, v122
	v_permlane32_swap_b32_e32 v121, v123
	v_permlane32_swap_b32_e32 v124, v126
	v_permlane32_swap_b32_e32 v125, v127
	v_add_f32_e32 v15, v15, v195
	v_fmac_f32_e32 v15, v192, v194
	v_mov_b32_e32 v192, v15
	s_add_i32 s0, s10, 0x8000
	s_and_b32 s0, s0, 0x18000
	v_add_u32_e32 v13, s0, v191
	ds_read_b64_tr_b16 v[128:129], v13 offset:0
	ds_read_b64_tr_b16 v[130:131], v13 offset:2048
	ds_read_b64_tr_b16 v[132:133], v13 offset:512
	ds_read_b64_tr_b16 v[134:135], v13 offset:2560
	ds_read_b64_tr_b16 v[136:137], v13 offset:1024
	ds_read_b64_tr_b16 v[138:139], v13 offset:3072
	ds_read_b64_tr_b16 v[140:141], v13 offset:1536
	ds_read_b64_tr_b16 v[142:143], v13 offset:3584
	s_branch .Lnl_J_o

.Lnl_nors_ob:
	v_max_f32_e32 v206, v113, v113
	v_max_f32_e32 v207, v112, v112
	v_max_f32_e32 v206, v207, v206
	v_max3_f32 v206, v206, v114, v115
	v_max3_f32 v206, v206, v116, v117
	v_max3_f32 v206, v206, v118, v119
	v_max3_f32 v206, v206, v120, v121
	v_max3_f32 v206, v206, v122, v123
	v_max3_f32 v206, v206, v124, v125
	v_max3_f32 v206, v206, v126, v127
	v_max3_f32 v206, v206, v128, v129
	v_max3_f32 v206, v206, v130, v131
	v_max3_f32 v206, v206, v132, v133
	v_max3_f32 v206, v206, v134, v135
	v_max3_f32 v206, v206, v136, v137
	v_max3_f32 v206, v206, v138, v139
	v_max3_f32 v206, v206, v140, v141
	v_max3_f32 v206, v206, v142, v143
	v_mov_b32_e32 v207, v206
	s_nop 1
	v_permlane32_swap_b32_e32 v206, v207
	v_max_f32_e32 v207, v207, v207
	v_max_f32_e32 v206, v206, v206
	v_max_f32_e32 v206, v206, v207
	v_sub_f32_e32 v207, v206, v193
	v_cmp_ge_f32_e64 s[0:1], s27, v207
	v_max_f32_e32 v206, v206, v206
	v_max_f32_e32 v207, v193, v193
	v_max_f32_e32 v206, v207, v206
	s_cmp_eq_u64 s[0:1], exec
	s_cselect_b64 s[0:1], -1, 0
	v_cndmask_b32_e64 v14, v206, v193, s[0:1]
	v_mul_f32_e32 v207, 0xbe38aa3b, v14
	v_fmamk_f32 v174, v112, 0x3e38aa3b, v207
	v_exp_f32_e32 v112, v174
	v_fmamk_f32 v174, v113, 0x3e38aa3b, v207
	v_exp_f32_e32 v113, v174
	v_fmamk_f32 v174, v114, 0x3e38aa3b, v207
	v_exp_f32_e32 v114, v174
	v_fmamk_f32 v174, v115, 0x3e38aa3b, v207
	v_exp_f32_e32 v115, v174
	v_fmamk_f32 v174, v116, 0x3e38aa3b, v207
	v_exp_f32_e32 v116, v174
	v_fmamk_f32 v174, v117, 0x3e38aa3b, v207
	v_exp_f32_e32 v117, v174
	v_fmamk_f32 v174, v118, 0x3e38aa3b, v207
	v_exp_f32_e32 v118, v174
	v_fmamk_f32 v174, v119, 0x3e38aa3b, v207
	v_exp_f32_e32 v119, v174
	v_fmamk_f32 v174, v120, 0x3e38aa3b, v207
	v_exp_f32_e32 v120, v174
	v_fmamk_f32 v174, v121, 0x3e38aa3b, v207
	v_exp_f32_e32 v121, v174
	v_fmamk_f32 v174, v122, 0x3e38aa3b, v207
	v_exp_f32_e32 v122, v174
	v_fmamk_f32 v174, v123, 0x3e38aa3b, v207
	v_exp_f32_e32 v123, v174
	v_fmamk_f32 v174, v124, 0x3e38aa3b, v207
	v_exp_f32_e32 v124, v174
	v_fmamk_f32 v174, v125, 0x3e38aa3b, v207
	v_exp_f32_e32 v125, v174
	v_fmamk_f32 v174, v126, 0x3e38aa3b, v207
	v_exp_f32_e32 v126, v174
	v_fmamk_f32 v174, v127, 0x3e38aa3b, v207
	v_exp_f32_e32 v127, v174
	v_fmamk_f32 v174, v128, 0x3e38aa3b, v207
	v_exp_f32_e32 v128, v174
	v_fmamk_f32 v174, v129, 0x3e38aa3b, v207
	v_exp_f32_e32 v129, v174
	v_fmamk_f32 v174, v130, 0x3e38aa3b, v207
	v_exp_f32_e32 v130, v174
	v_fmamk_f32 v174, v131, 0x3e38aa3b, v207
	v_exp_f32_e32 v131, v174
	v_fmamk_f32 v174, v132, 0x3e38aa3b, v207
	ds_read_b64_tr_b16 v[160:161], v13 offset:4096
	ds_read_b64_tr_b16 v[162:163], v13 offset:6144
	ds_read_b64_tr_b16 v[182:183], v13 offset:4608
	ds_read_b64_tr_b16 v[184:185], v13 offset:6656
	ds_read_b64_tr_b16 v[198:199], v13 offset:5120
	ds_read_b64_tr_b16 v[200:201], v13 offset:7168
	ds_read_b64_tr_b16 v[202:203], v13 offset:5632
	ds_read_b64_tr_b16 v[204:205], v13 offset:7680
	v_exp_f32_e32 v132, v174
	v_fmamk_f32 v174, v133, 0x3e38aa3b, v207
	s_waitcnt lgkmcnt(8)
	v_exp_f32_e32 v133, v174
	v_fmamk_f32 v174, v134, 0x3e38aa3b, v207
	v_exp_f32_e32 v134, v174
	v_mfma_f32_32x32x16_bf16 v[64:79], v[96:99], v[80:83], v[64:79]
	v_fmamk_f32 v174, v135, 0x3e38aa3b, v207
	v_exp_f32_e32 v135, v174
	v_mfma_f32_32x32x16_bf16 v[48:63], v[100:103], v[80:83], v[48:63]
	v_fmamk_f32 v174, v136, 0x3e38aa3b, v207
	v_exp_f32_e32 v136, v174
	v_fmamk_f32 v174, v137, 0x3e38aa3b, v207
	v_mfma_f32_32x32x16_bf16 v[32:47], v[104:107], v[80:83], v[32:47]
	v_exp_f32_e32 v137, v174
	v_fmamk_f32 v174, v138, 0x3e38aa3b, v207
	v_mfma_f32_32x32x16_bf16 v[16:31], v[108:111], v[80:83], v[16:31]
	v_exp_f32_e32 v138, v174
	v_fmamk_f32 v174, v139, 0x3e38aa3b, v207
	v_exp_f32_e32 v139, v174
	ds_read_b64_tr_b16 v[96:97], v13 offset:8192
	ds_read_b64_tr_b16 v[98:99], v13 offset:10240
	ds_read_b64_tr_b16 v[100:101], v13 offset:8704
	ds_read_b64_tr_b16 v[102:103], v13 offset:10752
	ds_read_b64_tr_b16 v[104:105], v13 offset:9216
	ds_read_b64_tr_b16 v[106:107], v13 offset:11264
	ds_read_b64_tr_b16 v[108:109], v13 offset:9728
	ds_read_b64_tr_b16 v[110:111], v13 offset:11776
	v_fmamk_f32 v174, v140, 0x3e38aa3b, v207
	v_exp_f32_e32 v140, v174
	s_waitcnt lgkmcnt(8)
	v_fmamk_f32 v174, v141, 0x3e38aa3b, v207
	v_exp_f32_e32 v141, v174
	v_fmamk_f32 v174, v142, 0x3e38aa3b, v207
	v_mfma_f32_32x32x16_bf16 v[64:79], v[160:163], v[84:87], v[64:79]
	v_exp_f32_e32 v142, v174
	v_fmamk_f32 v174, v143, 0x3e38aa3b, v207
	v_exp_f32_e32 v143, v174
	v_mfma_f32_32x32x16_bf16 v[48:63], v[182:185], v[84:87], v[48:63]
	v_sub_f32_e32 v206, v193, v206
	v_mul_f32_e32 v206, 0x3e38aa3b, v206
	v_mfma_f32_32x32x16_bf16 v[32:47], v[198:201], v[84:87], v[32:47]
	v_exp_f32_e32 v206, v206
	v_add_f32_e32 v207, 0, v112
	v_cndmask_b32_e64 v194, v206, 1.0, s[0:1]
	v_mfma_f32_32x32x16_bf16 v[16:31], v[202:205], v[84:87], v[16:31]
	v_mov_b32_e32 v193, v14
	v_add_f32_e32 v207, v113, v207
	ds_read_b64_tr_b16 v[160:161], v13 offset:12288
	ds_read_b64_tr_b16 v[162:163], v13 offset:14336
	ds_read_b64_tr_b16 v[182:183], v13 offset:12800
	ds_read_b64_tr_b16 v[184:185], v13 offset:14848
	ds_read_b64_tr_b16 v[198:199], v13 offset:13312
	ds_read_b64_tr_b16 v[200:201], v13 offset:15360
	ds_read_b64_tr_b16 v[202:203], v13 offset:13824
	ds_read_b64_tr_b16 v[204:205], v13 offset:15872
	v_add_f32_e32 v207, v114, v207
	v_add_f32_e32 v207, v115, v207
	v_add_f32_e32 v207, v116, v207
	s_waitcnt lgkmcnt(8)
	v_add_f32_e32 v207, v117, v207
	v_add_f32_e32 v207, v118, v207
	v_mfma_f32_32x32x16_bf16 v[64:79], v[96:99], v[88:91], v[64:79]
	v_add_f32_e32 v207, v119, v207
	v_add_f32_e32 v207, v120, v207
	v_add_f32_e32 v207, v121, v207
	v_mfma_f32_32x32x16_bf16 v[48:63], v[100:103], v[88:91], v[48:63]
	v_add_f32_e32 v207, v122, v207
	v_add_f32_e32 v207, v123, v207
	v_add_f32_e32 v207, v124, v207
	v_mfma_f32_32x32x16_bf16 v[32:47], v[104:107], v[88:91], v[32:47]
	v_add_f32_e32 v207, v125, v207
	v_add_f32_e32 v207, v126, v207
	v_mfma_f32_32x32x16_bf16 v[16:31], v[108:111], v[88:91], v[16:31]
	v_add_f32_e32 v207, v127, v207
	v_add_f32_e32 v207, v128, v207
	v_add_f32_e32 v207, v129, v207
	s_waitcnt lgkmcnt(0)
	v_add_f32_e32 v207, v130, v207
	v_add_f32_e32 v207, v131, v207
	v_mfma_f32_32x32x16_bf16 v[64:79], v[160:163], v[92:95], v[64:79]
	v_add_f32_e32 v207, v132, v207
	v_add_f32_e32 v207, v133, v207
	v_add_f32_e32 v207, v134, v207
	v_mfma_f32_32x32x16_bf16 v[48:63], v[182:185], v[92:95], v[48:63]
	v_add_f32_e32 v207, v135, v207
	v_add_f32_e32 v207, v136, v207
	v_mfma_f32_32x32x16_bf16 v[32:47], v[198:201], v[92:95], v[32:47]
	v_add_f32_e32 v207, v137, v207
	v_add_f32_e32 v207, v138, v207
	v_add_f32_e32 v207, v139, v207
	v_mfma_f32_32x32x16_bf16 v[16:31], v[202:205], v[92:95], v[16:31]
	v_add_f32_e32 v207, v140, v207
	v_add_f32_e32 v207, v141, v207
	s_add_i32 s6, s10, 0x10000
	s_and_b32 s6, s6, 0x18000
	v_add_u32_e32 v0, s6, v175
	ds_read_b128 v[2:5], v0 offset:0
	ds_read_b128 v[6:9], v0 offset:8192
	v_add_u32_e32 v0, s6, v176
	ds_read_b128 v[10:13], v0 offset:0
	ds_read_b128 v[160:163], v0 offset:8192
	v_add_f32_e32 v207, v142, v207
	v_add_f32_e32 v15, v143, v207
	v_mov_b32_e32 v195, v15
	s_waitcnt lgkmcnt(0)
	v_mfma_f32_32x32x16_bf16 v[80:95], v[2:5], v[144:147], 0
	v_cvt_pk_bf16_f32 v112, v112, v113
	v_cvt_pk_bf16_f32 v113, v114, v115
	v_cvt_pk_bf16_f32 v114, v116, v117
	v_add_u32_e32 v0, s6, v177
	ds_read_b128 v[2:5], v0 offset:0
	v_mfma_f32_32x32x16_bf16 v[96:111], v[6:9], v[144:147], 0
	ds_read_b128 v[6:9], v0 offset:8192
	v_cvt_pk_bf16_f32 v115, v118, v119
	v_cvt_pk_bf16_f32 v116, v120, v121
	v_add_u32_e32 v0, s6, v189
	v_mfma_f32_32x32x16_bf16 v[80:95], v[10:13], v[148:151], v[80:95]
	ds_read_b128 v[10:13], v0 offset:0
	ds_read_b128 v[182:185], v0 offset:8192
	v_cvt_pk_bf16_f32 v117, v122, v123
	v_cvt_pk_bf16_f32 v118, v124, v125
	v_cvt_pk_bf16_f32 v119, v126, v127
	s_waitcnt lgkmcnt(0)
	v_mfma_f32_32x32x16_bf16 v[96:111], v[160:163], v[148:151], v[96:111]
	v_cvt_pk_bf16_f32 v120, v128, v129
	v_cvt_pk_bf16_f32 v121, v130, v131
	v_mfma_f32_32x32x16_bf16 v[80:95], v[2:5], v[152:155], v[80:95]
	v_cvt_pk_bf16_f32 v122, v132, v133
	v_cvt_pk_bf16_f32 v123, v134, v135
	v_cvt_pk_bf16_f32 v124, v136, v137
	v_mfma_f32_32x32x16_bf16 v[96:111], v[6:9], v[152:155], v[96:111]
	v_cvt_pk_bf16_f32 v125, v138, v139
	v_cvt_pk_bf16_f32 v126, v140, v141
	v_mfma_f32_32x32x16_bf16 v[80:95], v[10:13], v[156:159], v[80:95]
	v_cvt_pk_bf16_f32 v127, v142, v143
	s_nop 1
	v_permlane32_swap_b32_e32 v15, v195
	v_mfma_f32_32x32x16_bf16 v[96:111], v[182:185], v[156:159], v[96:111]
	v_permlane32_swap_b32_e32 v112, v114
	v_permlane32_swap_b32_e32 v113, v115
	v_permlane32_swap_b32_e32 v116, v118
	v_permlane32_swap_b32_e32 v117, v119
	v_permlane32_swap_b32_e32 v120, v122
	v_permlane32_swap_b32_e32 v121, v123
	v_permlane32_swap_b32_e32 v124, v126
	v_permlane32_swap_b32_e32 v125, v127
	v_add_f32_e32 v15, v15, v195
	v_fmac_f32_e32 v15, v192, v194
	v_mov_b32_e32 v192, v15
	s_add_i32 s0, s10, 0x8000
	s_and_b32 s0, s0, 0x18000
	v_add_u32_e32 v13, s0, v191
	ds_read_b64_tr_b16 v[128:129], v13 offset:0
	ds_read_b64_tr_b16 v[130:131], v13 offset:2048
	ds_read_b64_tr_b16 v[132:133], v13 offset:512
	ds_read_b64_tr_b16 v[134:135], v13 offset:2560
	ds_read_b64_tr_b16 v[136:137], v13 offset:1024
	ds_read_b64_tr_b16 v[138:139], v13 offset:3072
	ds_read_b64_tr_b16 v[140:141], v13 offset:1536
	ds_read_b64_tr_b16 v[142:143], v13 offset:3584
.Lnl_J_o:
.Lnl_qo:
	s_add_i32 s11, s11, 2
	s_add_i32 s10, s10, 0x10000
	s_add_u32 s78, s78, 0xc0000
	s_addc_u32 s79, s79, 0
	s_cmp_lt_i32 s11, s9
	s_cbranch_scc1 .LBB0_588
	s_cmp_lt_i32 s8, s9
	s_cbranch_scc1 .Lnl_done
	v_cmp_gt_f32_e32 vcc, 1.0, v194
	s_cbranch_vccz .Lnl_nors_dr
	v_pk_mul_f32 v[78:79], v[78:79], v[194:195] op_sel_hi:[1,0]
	v_pk_mul_f32 v[76:77], v[76:77], v[194:195] op_sel_hi:[1,0]
	v_pk_mul_f32 v[74:75], v[74:75], v[194:195] op_sel_hi:[1,0]
	v_pk_mul_f32 v[72:73], v[72:73], v[194:195] op_sel_hi:[1,0]
	v_pk_mul_f32 v[70:71], v[70:71], v[194:195] op_sel_hi:[1,0]
	v_pk_mul_f32 v[68:69], v[68:69], v[194:195] op_sel_hi:[1,0]
	v_pk_mul_f32 v[66:67], v[66:67], v[194:195] op_sel_hi:[1,0]
	v_pk_mul_f32 v[64:65], v[64:65], v[194:195] op_sel_hi:[1,0]
	v_pk_mul_f32 v[62:63], v[62:63], v[194:195] op_sel_hi:[1,0]
	v_pk_mul_f32 v[60:61], v[60:61], v[194:195] op_sel_hi:[1,0]
	v_pk_mul_f32 v[58:59], v[58:59], v[194:195] op_sel_hi:[1,0]
	v_pk_mul_f32 v[56:57], v[56:57], v[194:195] op_sel_hi:[1,0]
	v_pk_mul_f32 v[54:55], v[54:55], v[194:195] op_sel_hi:[1,0]
	v_pk_mul_f32 v[52:53], v[52:53], v[194:195] op_sel_hi:[1,0]
	v_pk_mul_f32 v[50:51], v[50:51], v[194:195] op_sel_hi:[1,0]
	v_pk_mul_f32 v[48:49], v[48:49], v[194:195] op_sel_hi:[1,0]
	v_pk_mul_f32 v[46:47], v[46:47], v[194:195] op_sel_hi:[1,0]
	v_pk_mul_f32 v[44:45], v[44:45], v[194:195] op_sel_hi:[1,0]
	v_pk_mul_f32 v[42:43], v[42:43], v[194:195] op_sel_hi:[1,0]
	v_pk_mul_f32 v[40:41], v[40:41], v[194:195] op_sel_hi:[1,0]
	v_pk_mul_f32 v[38:39], v[38:39], v[194:195] op_sel_hi:[1,0]
	v_pk_mul_f32 v[36:37], v[36:37], v[194:195] op_sel_hi:[1,0]
	v_pk_mul_f32 v[34:35], v[34:35], v[194:195] op_sel_hi:[1,0]
	v_pk_mul_f32 v[32:33], v[32:33], v[194:195] op_sel_hi:[1,0]
	v_pk_mul_f32 v[30:31], v[30:31], v[194:195] op_sel_hi:[1,0]
	v_pk_mul_f32 v[28:29], v[28:29], v[194:195] op_sel_hi:[1,0]
	v_pk_mul_f32 v[26:27], v[26:27], v[194:195] op_sel_hi:[1,0]
	v_pk_mul_f32 v[24:25], v[24:25], v[194:195] op_sel_hi:[1,0]
	v_pk_mul_f32 v[22:23], v[22:23], v[194:195] op_sel_hi:[1,0]
	v_pk_mul_f32 v[20:21], v[20:21], v[194:195] op_sel_hi:[1,0]
	v_pk_mul_f32 v[18:19], v[18:19], v[194:195] op_sel_hi:[1,0]
	v_pk_mul_f32 v[16:17], v[16:17], v[194:195] op_sel_hi:[1,0]
.Lnl_nors_dr:
	ds_read_b64_tr_b16 v[160:161], v13 offset:4096
	ds_read_b64_tr_b16 v[162:163], v13 offset:6144
	ds_read_b64_tr_b16 v[182:183], v13 offset:4608
	ds_read_b64_tr_b16 v[184:185], v13 offset:6656
	ds_read_b64_tr_b16 v[198:199], v13 offset:5120
	ds_read_b64_tr_b16 v[200:201], v13 offset:7168
	ds_read_b64_tr_b16 v[202:203], v13 offset:5632
	ds_read_b64_tr_b16 v[204:205], v13 offset:7680
	s_waitcnt lgkmcnt(8)
	v_mfma_f32_32x32x16_bf16 v[64:79], v[128:131], v[112:115], v[64:79]
	v_mfma_f32_32x32x16_bf16 v[48:63], v[132:135], v[112:115], v[48:63]
	v_mfma_f32_32x32x16_bf16 v[32:47], v[136:139], v[112:115], v[32:47]
	v_mfma_f32_32x32x16_bf16 v[16:31], v[140:143], v[112:115], v[16:31]
	ds_read_b64_tr_b16 v[128:129], v13 offset:8192
	ds_read_b64_tr_b16 v[130:131], v13 offset:10240
	ds_read_b64_tr_b16 v[132:133], v13 offset:8704
	ds_read_b64_tr_b16 v[134:135], v13 offset:10752
	ds_read_b64_tr_b16 v[136:137], v13 offset:9216
	ds_read_b64_tr_b16 v[138:139], v13 offset:11264
	ds_read_b64_tr_b16 v[140:141], v13 offset:9728
	ds_read_b64_tr_b16 v[142:143], v13 offset:11776
	s_waitcnt lgkmcnt(8)
	v_mfma_f32_32x32x16_bf16 v[64:79], v[160:163], v[116:119], v[64:79]
	v_mfma_f32_32x32x16_bf16 v[48:63], v[182:185], v[116:119], v[48:63]
	v_mfma_f32_32x32x16_bf16 v[32:47], v[198:201], v[116:119], v[32:47]
	v_mfma_f32_32x32x16_bf16 v[16:31], v[202:205], v[116:119], v[16:31]
	ds_read_b64_tr_b16 v[160:161], v13 offset:12288
	ds_read_b64_tr_b16 v[162:163], v13 offset:14336
	ds_read_b64_tr_b16 v[182:183], v13 offset:12800
	ds_read_b64_tr_b16 v[184:185], v13 offset:14848
	ds_read_b64_tr_b16 v[198:199], v13 offset:13312
	ds_read_b64_tr_b16 v[200:201], v13 offset:15360
	ds_read_b64_tr_b16 v[202:203], v13 offset:13824
	ds_read_b64_tr_b16 v[204:205], v13 offset:15872
	s_waitcnt lgkmcnt(8)
	v_mfma_f32_32x32x16_bf16 v[64:79], v[128:131], v[120:123], v[64:79]
	v_mfma_f32_32x32x16_bf16 v[48:63], v[132:135], v[120:123], v[48:63]
	v_mfma_f32_32x32x16_bf16 v[32:47], v[136:139], v[120:123], v[32:47]
	v_mfma_f32_32x32x16_bf16 v[16:31], v[140:143], v[120:123], v[16:31]
	s_waitcnt lgkmcnt(0)
	v_mfma_f32_32x32x16_bf16 v[64:79], v[160:163], v[124:127], v[64:79]
	v_mfma_f32_32x32x16_bf16 v[48:63], v[182:185], v[124:127], v[48:63]
	v_mfma_f32_32x32x16_bf16 v[32:47], v[198:201], v[124:127], v[32:47]
	v_mfma_f32_32x32x16_bf16 v[16:31], v[202:205], v[124:127], v[16:31]

	.amdhsa_kernel _Z8yoco_fwd4Args
		.amdhsa_group_segment_fixed_size 0
		.amdhsa_private_segment_fixed_size 0
		.amdhsa_kernarg_size 464
		.amdhsa_user_sgpr_count 2
		.amdhsa_user_sgpr_dispatch_ptr 0
		.amdhsa_user_sgpr_queue_ptr 0
		.amdhsa_user_sgpr_kernarg_segment_ptr 1
		.amdhsa_user_sgpr_dispatch_id 0
		.amdhsa_user_sgpr_kernarg_preload_length 0
		.amdhsa_user_sgpr_kernarg_preload_offset 0
		.amdhsa_user_sgpr_private_segment_size 0
		.amdhsa_uses_dynamic_stack 0
		.amdhsa_enable_private_segment 0
		.amdhsa_system_sgpr_workgroup_id_x 1
		.amdhsa_system_sgpr_workgroup_id_y 0
		.amdhsa_system_sgpr_workgroup_id_z 0
		.amdhsa_system_sgpr_workgroup_info 0
		.amdhsa_system_vgpr_workitem_id 2
		.amdhsa_next_free_vgpr 256
		.amdhsa_next_free_sgpr 99
		.amdhsa_accum_offset 256
		.amdhsa_reserve_vcc 1
		.amdhsa_float_round_mode_32 0
		.amdhsa_float_round_mode_16_64 0
		.amdhsa_float_denorm_mode_32 3
		.amdhsa_float_denorm_mode_16_64 3
		.amdhsa_dx10_clamp 1
		.amdhsa_ieee_mode 1
		.amdhsa_fp16_overflow 0
		.amdhsa_tg_split 0
		.amdhsa_exception_fp_ieee_invalid_op 0
		.amdhsa_exception_fp_denorm_src 0
		.amdhsa_exception_fp_ieee_div_zero 0
		.amdhsa_exception_fp_ieee_overflow 0
		.amdhsa_exception_fp_ieee_underflow 0
		.amdhsa_exception_fp_ieee_inexact 0
		.amdhsa_exception_int_div_zero 0
	.end_amdhsa_kernel

amdhsa.kernels:
  - .agpr_count:     0
    .args:
      - .offset:         0
        .size:           208
        .value_kind:     by_value
      - .offset:         208
        .size:           4
        .value_kind:     hidden_block_count_x
      - .offset:         212
        .size:           4
        .value_kind:     hidden_block_count_y
      - .offset:         216
        .size:           4
        .value_kind:     hidden_block_count_z
      - .offset:         220
        .size:           2
        .value_kind:     hidden_group_size_x
      - .offset:         222
        .size:           2
        .value_kind:     hidden_group_size_y
      - .offset:         224
        .size:           2
        .value_kind:     hidden_group_size_z
      - .offset:         226
        .size:           2
        .value_kind:     hidden_remainder_x
      - .offset:         228
        .size:           2
        .value_kind:     hidden_remainder_y
      - .offset:         230
        .size:           2
        .value_kind:     hidden_remainder_z
      - .offset:         248
        .size:           8
        .value_kind:     hidden_global_offset_x
      - .offset:         256
        .size:           8
        .value_kind:     hidden_global_offset_y
      - .offset:         264
        .size:           8
        .value_kind:     hidden_global_offset_z
      - .offset:         272
        .size:           2
        .value_kind:     hidden_grid_dims
      - .offset:         296
        .size:           8
        .value_kind:     hidden_multigrid_sync_arg
      - .offset:         328
        .size:           4
        .value_kind:     hidden_dynamic_lds_size
    .group_segment_fixed_size: 0
    .kernarg_segment_align: 8
    .kernarg_segment_size: 464
    .language:       OpenCL C
    .language_version:
      - 2
      - 0
    .max_flat_workgroup_size: 512
    .name:           _Z8yoco_fwd4Args
    .private_segment_fixed_size: 0
    .sgpr_count:     105
    .sgpr_spill_count: 195
    .symbol:         _Z8yoco_fwd4Args.kd
    .uniform_work_group_size: 1
    .uses_dynamic_stack: false
    .vgpr_count:     256
    .vgpr_spill_count: 0
    .wavefront_size: 64
